# lever 1 (counted vmcnt across the tile boundary): in-proj/proj/ffn_up: first k-iteration of every non-first tile is a peeled copy whose ring waits allow the previous epilogue's stores to stay outstand
# speedup vs baseline: 1.0030x; 1.0030x over previous
; #define PG8_STAGE(bufoff, gbase, voff) do { _Pragma("unroll") for (int _i = 0; _i < 2; ++_i) \
;         __builtin_amdgcn_global_load_lds((const unsigned*)((const char*)(gbase) + (voff)[_i]), (LAS unsigned*)(lds + (bufoff) + ldsw + _i * 8192), 16, 0, 0); } while (0)
; #define PG8_WAIT_V(n) asm volatile("s_waitcnt vmcnt(" #n ")" ::: "memory")
; #define PG8_BAR __builtin_amdgcn_s_barrier()
;     __device__ __forceinline__ const char* aptr(const Unit& u) const { return (const char*)A + (size_t)u.pm * 256 * K * 2; }
;     __device__ __forceinline__ const char* bptr(const Unit& u) const { return (const char*)Bt + (size_t)u.pn * 256 * K * 2; }
; template <class Epi, class Sched, bool ALIGN_EPI = true>
; __device__ __forceinline__ void gemm_phase(LAS unsigned char* lds, const int wave_s, const int K, const Sched& S, const Epi& E) {
;     ...
;     const char* cA = S.aptr(cur); const char* cB = S.bptr(cur);
;     PG8_STAGE(PG8_SB(0, 0), cB, voffB); PG8_STAGE(PG8_SB(0, 1), cB + hstep, voffB); PG8_STAGE(PG8_SA(0, 0), cA, voffA); PG8_STAGE(PG8_SA(0, 1), cA + hstep, voffA);
;     if (wr == 1) PG8_BAR;
;     PG8_WAIT_V(2); PG8_BAR;
;     PG8_STAGE(PG8_SB(1, 0), cB + kstep, voffB); PG8_STAGE(PG8_SA(1, 0), cA + kstep, voffA); PG8_STAGE(PG8_SB(1, 1), cB + hstep + kstep, voffB);
;     PG8_WAIT_V(6); PG8_BAR;
;     for (;;) {
.LBB0_150:
	v_and_b32_e32 v17, 15, v16
	v_readlane_b32 s14, v253, 6
	v_lshrrev_b32_e32 v18, 1, v16
	v_and_b32_e32 v18, 24, v18
	v_or_b32_e32 v142, s14, v17
	s_add_u32 s12, s10, 0xad00000
	v_lshlrev_b32_e32 v19, 6, v142
	v_lshlrev_b32_e32 v20, 1, v18
	s_movk_i32 s14, 0x3c0
	v_lshlrev_b32_e32 v21, 2, v142
	s_addc_u32 s13, s11, 0
	v_and_or_b32 v19, v19, s14, v20
	v_and_b32_e32 v21, 32, v21
	v_readlane_b32 s14, v253, 7
	v_lshlrev_b32_e32 v16, 2, v16
	v_lshl_add_u64 v[2:3], v[2:3], 0, s[22:23]
	s_add_i32 m0, s18, 0x18000
	v_bitop3_b32 v19, v19, s14, v21 bitop3:0xde
	v_lshl_or_b32 v17, v17, 6, v20
	v_and_b32_e32 v16, 32, v16
	v_readlane_b32 s14, v253, 19
	s_waitcnt vmcnt(2)
	s_barrier
	global_load_lds_dwordx4 v[2:3], off
	v_lshl_add_u64 v[2:3], v[4:5], 0, s[22:23]
	s_add_i32 m0, s18, 0x1a000
	s_add_i32 s28, s18, 0x8000
	s_add_i32 s30, s18, 0xa000
	v_bitop3_b32 v143, v17, s14, v16 bitop3:0xde
	global_load_lds_dwordx4 v[2:3], off
	v_lshl_add_u64 v[2:3], v[6:7], 0, s[22:23]
	s_mov_b32 m0, s28
	s_add_u32 s14, s50, 0x40080
	global_load_lds_dwordx4 v[2:3], off
	v_lshl_add_u64 v[2:3], v[8:9], 0, s[22:23]
	s_mov_b32 m0, s30
	s_addc_u32 s15, s51, 0
	global_load_lds_dwordx4 v[2:3], off
	v_lshl_add_u64 v[2:3], s[14:15], 0, v[0:1]
	s_add_i32 m0, s18, 0x1c000
	s_ashr_i32 s36, s29, 31
	global_load_lds_dwordx4 v[2:3], off
	v_lshl_add_u64 v[2:3], s[14:15], 0, v[130:131]
	s_add_i32 m0, s18, 0x1e000
	v_readlane_b32 s14, v253, 18
	global_load_lds_dwordx4 v[2:3], off
	v_lshlrev_b32_e32 v2, 14, v13
	v_and_b32_e32 v2, 0xffff8000, v2
	v_lshl_add_u32 v2, v14, 11, v2
	v_and_b32_e32 v3, 1, v13
	v_lshl_or_b32 v2, v3, 6, v2
	v_lshl_add_u32 v136, v15, 1, v2
	v_lshlrev_b32_e32 v2, 14, v10
	v_or_b32_e32 v144, s14, v18
	v_and_b32_e32 v2, 0xffff8000, v2
	v_readlane_b32 s14, v254, 44
	s_waitcnt vmcnt(6)
	v_lshl_add_u32 v2, v11, 11, v2
	v_and_b32_e32 v3, 1, v10
	v_readlane_b32 s15, v254, 45
	v_lshl_or_b32 v2, v3, 6, v2
	s_mov_b32 s54, s14
	v_readlane_b32 s14, v254, 40
	v_mov_b32_e32 v137, v1
	v_lshl_add_u32 v138, v12, 1, v2
	v_mov_b32_e32 v139, v1
	s_mov_b32 s39, 0
	v_add_u32_e32 v145, 0, v19
	s_mov_b32 s55, s14
	s_barrier
	v_readlane_b32 s15, v254, 41
	s_mov_b32 s100, 0
	s_branch .LBB0_153

; #define PG8_BAR __builtin_amdgcn_s_barrier()
; template <class Epi, class Sched, bool ALIGN_EPI = true>
; __device__ __forceinline__ void gemm_phase(LAS unsigned char* lds, const int wave_s, const int K, const Sched& S, const Epi& E) {
;     ...
;         if (!has_next) break;
; #pragma unroll
;         for (int a = 0; a < 2; ++a)
; #pragma unroll
;             for (int b = 0; b < 2; ++b)
; #pragma unroll
;                 for (int m = 0; m < 4; ++m)
; #pragma unroll
;                     for (int n = 0; n < 2; ++n) acc[a][b][m][n] = (f32x4){0.f, 0.f, 0.f, 0.f};
;         cur = nxt; cA = nA; cB = nB; ++ui;
;         if constexpr (ALIGN_EPI) { if (wr == 1) PG8_BAR; }
.LBB0_152:
	s_andn2_b64 vcc, exec, s[42:43]
	s_mov_b32 s54, s14
	s_mov_b32 s55, s34
	s_mov_b64 s[50:51], s[46:47]
	s_mov_b64 s[48:49], s[44:45]
	s_cbranch_vccz .LBB0_166
	s_mov_b32 s100, 1

; #define PG8_STAGE(bufoff, gbase, voff) do { _Pragma("unroll") for (int _i = 0; _i < 2; ++_i) \
;         __builtin_amdgcn_global_load_lds((const unsigned*)((const char*)(gbase) + (voff)[_i]), (LAS unsigned*)(lds + (bufoff) + ldsw + _i * 8192), 16, 0, 0); } while (0)
; #define PG8_LDA(dst, b, h) do { _Pragma("unroll") for (int m = 0; m < 4; ++m) _Pragma("unroll") for (int k = 0; k < 2; ++k) dst[m][k] = *(const LAS bf16x8*)(lds + PG8_SA(b, h) + aoff + m * 2048 + k * 1024); } while (0)
; #define PG8_LDB(dst, b, h) do { _Pragma("unroll") for (int n = 0; n < 2; ++n) _Pragma("unroll") for (int k = 0; k < 2; ++k) dst[n][k] = *(const LAS bf16x8*)(lds + PG8_SB(b, h) + boff + n * 2048 + k * 1024); } while (0)
; #define PG8_MMA(ai, bj, At, Bt) do { __builtin_amdgcn_s_setprio(1); _Pragma("unroll") for (int m = 0; m < 4; ++m) _Pragma("unroll") for (int n = 0; n < 2; ++n) _Pragma("unroll") for (int k = 0; k < 2; ++k) \
;         acc[ai][bj][m][n] = __builtin_amdgcn_mfma_f32_16x16x32_bf16(Bt[n][k], At[m][k], acc[ai][bj][m][n], 0, 0, 0); __builtin_amdgcn_s_setprio(0); } while (0)
; #define PG8_WAIT_V(n) asm volatile("s_waitcnt vmcnt(" #n ")" ::: "memory")
; #define PG8_WAIT_L(n) asm volatile("s_waitcnt lgkmcnt(" #n ")" ::: "memory")
; #define PG8_BAR __builtin_amdgcn_s_barrier()
; #define PG8_SCHED __builtin_amdgcn_sched_barrier(0)
; template <class Epi, class Sched, bool ALIGN_EPI = true>
; __device__ __forceinline__ void gemm_phase(LAS unsigned char* lds, const int wave_s, const int K, const Sched& S, const Epi& E) {
;     ...
;             PG8_LDB(B0, 0, 0); PG8_LDB(B1, 0, 1); PG8_SCHED; PG8_LDA(At, 0, 0); PG8_STAGE(PG8_SA(1, 1), a1 + hstep, voffA);
;             PG8_WAIT_V(8); PG8_WAIT_L(0); PG8_BAR; PG8_MMA(0, 0, At, B0); PG8_MMA(0, 1, At, B1); PG8_BAR; PG8_SCHED;
;     ...
; #pragma unroll
;         for (int a = 0; a < 2; ++a)
; #pragma unroll
;             for (int b = 0; b < 2; ++b)
; #pragma unroll
;                 for (int m = 0; m < 4; ++m)
; #pragma unroll
;                     for (int n = 0; n < 2; ++n) acc[a][b][m][n] = (f32x4){0.f, 0.f, 0.f, 0.f};
;         cur = nxt; cA = nA; cB = nB; ++ui;
.LBB0_159:
	s_ashr_i32 s35, s34, 31
	s_lshl_b64 s[44:45], s[34:35], 19
	s_add_u32 s44, s4, s44
	s_addc_u32 s45, s5, s45
	s_and_b64 s[46:47], s[42:43], exec
	s_cselect_b32 s35, s45, s49
	s_cselect_b32 s56, s44, s48
	s_ashr_i32 s15, s14, 31
	s_lshl_b64 s[46:47], s[14:15], 19
	s_add_u32 s46, s7, s46
	s_addc_u32 s47, s16, s47
	s_and_b64 s[52:53], s[42:43], exec
	s_cselect_b32 s15, s47, s51
	s_cselect_b32 s57, s46, s50
	s_add_u32 s48, s48, 0x40080
	s_addc_u32 s49, s49, 0
	s_add_u32 s60, s50, 0x100
	v_mov_b32_e32 v2, 0
	s_addc_u32 s61, s51, 0
	s_mov_b32 s62, -2
	v_mov_b32_e32 v3, v2
	v_mov_b32_e32 v4, v2
	v_mov_b32_e32 v5, v2
	v_mov_b32_e32 v6, v2
	v_mov_b32_e32 v7, v2
	v_mov_b32_e32 v8, v2
	v_mov_b32_e32 v9, v2
	v_mov_b32_e32 v18, v2
	v_mov_b32_e32 v19, v2
	v_mov_b32_e32 v20, v2
	v_mov_b32_e32 v21, v2
	v_mov_b32_e32 v22, v2
	v_mov_b32_e32 v23, v2
	v_mov_b32_e32 v24, v2
	v_mov_b32_e32 v25, v2
	v_mov_b32_e32 v34, v2
	v_mov_b32_e32 v35, v2
	v_mov_b32_e32 v36, v2
	v_mov_b32_e32 v37, v2
	v_mov_b32_e32 v38, v2
	v_mov_b32_e32 v39, v2
	v_mov_b32_e32 v40, v2
	v_mov_b32_e32 v41, v2
	v_mov_b32_e32 v50, v2
	v_mov_b32_e32 v51, v2
	v_mov_b32_e32 v52, v2
	v_mov_b32_e32 v53, v2
	v_mov_b32_e32 v54, v2
	v_mov_b32_e32 v55, v2
	v_mov_b32_e32 v56, v2
	v_mov_b32_e32 v57, v2
	v_mov_b32_e32 v10, v2
	v_mov_b32_e32 v11, v2
	v_mov_b32_e32 v12, v2
	v_mov_b32_e32 v13, v2
	v_mov_b32_e32 v14, v2
	v_mov_b32_e32 v15, v2
	v_mov_b32_e32 v16, v2
	v_mov_b32_e32 v17, v2
	v_mov_b32_e32 v26, v2
	v_mov_b32_e32 v27, v2
	v_mov_b32_e32 v28, v2
	v_mov_b32_e32 v29, v2
	v_mov_b32_e32 v30, v2
	v_mov_b32_e32 v31, v2
	v_mov_b32_e32 v32, v2
	v_mov_b32_e32 v33, v2
	v_mov_b32_e32 v42, v2
	v_mov_b32_e32 v43, v2
	v_mov_b32_e32 v44, v2
	v_mov_b32_e32 v45, v2
	v_mov_b32_e32 v46, v2
	v_mov_b32_e32 v47, v2
	v_mov_b32_e32 v48, v2
	v_mov_b32_e32 v49, v2
	v_mov_b32_e32 v58, v2
	v_mov_b32_e32 v59, v2
	v_mov_b32_e32 v60, v2
	v_mov_b32_e32 v61, v2
	v_mov_b32_e32 v62, v2
	v_mov_b32_e32 v63, v2
	v_mov_b32_e32 v64, v2
	v_mov_b32_e32 v65, v2
	v_mov_b32_e32 v66, v2
	v_mov_b32_e32 v67, v2
	v_mov_b32_e32 v68, v2
	v_mov_b32_e32 v69, v2
	v_mov_b32_e32 v70, v2
	v_mov_b32_e32 v71, v2
	v_mov_b32_e32 v72, v2
	v_mov_b32_e32 v73, v2
	v_mov_b32_e32 v82, v2
	v_mov_b32_e32 v83, v2
	v_mov_b32_e32 v84, v2
	v_mov_b32_e32 v85, v2
	v_mov_b32_e32 v86, v2
	v_mov_b32_e32 v87, v2
	v_mov_b32_e32 v88, v2
	v_mov_b32_e32 v89, v2
	v_mov_b32_e32 v98, v2
	v_mov_b32_e32 v99, v2
	v_mov_b32_e32 v100, v2
	v_mov_b32_e32 v101, v2
	v_mov_b32_e32 v102, v2
	v_mov_b32_e32 v103, v2
	v_mov_b32_e32 v104, v2
	v_mov_b32_e32 v105, v2
	v_mov_b32_e32 v114, v2
	v_mov_b32_e32 v115, v2
	v_mov_b32_e32 v116, v2
	v_mov_b32_e32 v117, v2
	v_mov_b32_e32 v118, v2
	v_mov_b32_e32 v119, v2
	v_mov_b32_e32 v120, v2
	v_mov_b32_e32 v121, v2
	v_mov_b32_e32 v74, v2
	v_mov_b32_e32 v75, v2
	v_mov_b32_e32 v76, v2
	v_mov_b32_e32 v77, v2
	v_mov_b32_e32 v78, v2
	v_mov_b32_e32 v79, v2
	v_mov_b32_e32 v80, v2
	v_mov_b32_e32 v81, v2
	v_mov_b32_e32 v90, v2
	v_mov_b32_e32 v91, v2
	v_mov_b32_e32 v92, v2
	v_mov_b32_e32 v93, v2
	v_mov_b32_e32 v94, v2
	v_mov_b32_e32 v95, v2
	v_mov_b32_e32 v96, v2
	v_mov_b32_e32 v97, v2
	v_mov_b32_e32 v106, v2
	v_mov_b32_e32 v107, v2
	v_mov_b32_e32 v108, v2
	v_mov_b32_e32 v109, v2
	v_mov_b32_e32 v110, v2
	v_mov_b32_e32 v111, v2
	v_mov_b32_e32 v112, v2
	v_mov_b32_e32 v113, v2
	v_mov_b32_e32 v122, v2
	v_mov_b32_e32 v123, v2
	v_mov_b32_e32 v124, v2
	v_mov_b32_e32 v125, v2
	v_mov_b32_e32 v126, v2
	v_mov_b32_e32 v127, v2
	v_mov_b32_e32 v128, v2
	v_mov_b32_e32 v129, v2
	s_cmp_eq_u32 s100, 0
	s_cbranch_scc1 .LBB0_160
	s_add_u32 s50, s48, 0xfffc0080
	s_addc_u32 s51, s49, -1
	s_add_i32 s63, 0, 0x10000
	s_cmp_eq_u32 s62, 12
	s_cselect_b32 s53, s35, s51
	s_cselect_b32 s52, s56, s50
	v_add_u32_e32 v140, s63, v143
	s_cselect_b32 s51, s15, s61
	s_cselect_b32 s50, s57, s60
	s_add_i32 s68, 0, 0x14000
	ds_read_b128 v[146:149], v140
	ds_read_b128 v[150:153], v140 offset:1024
	ds_read_b128 v[154:157], v140 offset:2048
	ds_read_b128 v[166:169], v140 offset:3072
	v_add_u32_e32 v140, s68, v143
	ds_read_b128 v[170:173], v140
	ds_read_b128 v[174:177], v140 offset:1024
	ds_read_b128 v[178:181], v140 offset:2048
	ds_read_b128 v[182:185], v140 offset:3072
	v_lshl_add_u64 v[140:141], s[48:49], 0, v[136:137]
	s_add_i32 m0, s18, 0xc000
	ds_read_b128 v[186:189], v145
	ds_read_b128 v[202:205], v145 offset:1024
	ds_read_b128 v[206:209], v145 offset:2048
	ds_read_b128 v[210:213], v145 offset:3072
	ds_read_b128 v[214:217], v145 offset:4096
	ds_read_b128 v[218:221], v145 offset:5120
	ds_read_b128 v[222:225], v145 offset:6144
	ds_read_b128 v[226:229], v145 offset:7168
	global_load_lds_dwordx4 v[140:141], off
	v_lshl_add_u64 v[140:141], s[48:49], 0, v[138:139]
	s_add_i32 m0, s18, 0xe000
	s_nop 0
	global_load_lds_dwordx4 v[140:141], off
	s_waitcnt vmcnt(24)
	s_waitcnt lgkmcnt(0)
	s_barrier
; #define PG8_STAGE(bufoff, gbase, voff) do { _Pragma("unroll") for (int _i = 0; _i < 2; ++_i) \
;         __builtin_amdgcn_global_load_lds((const unsigned*)((const char*)(gbase) + (voff)[_i]), (LAS unsigned*)(lds + (bufoff) + ldsw + _i * 8192), 16, 0, 0); } while (0)
; #define PG8_LDA(dst, b, h) do { _Pragma("unroll") for (int m = 0; m < 4; ++m) _Pragma("unroll") for (int k = 0; k < 2; ++k) dst[m][k] = *(const LAS bf16x8*)(lds + PG8_SA(b, h) + aoff + m * 2048 + k * 1024); } while (0)
; #define PG8_MMA(ai, bj, At, Bt) do { __builtin_amdgcn_s_setprio(1); _Pragma("unroll") for (int m = 0; m < 4; ++m) _Pragma("unroll") for (int n = 0; n < 2; ++n) _Pragma("unroll") for (int k = 0; k < 2; ++k) \
;         acc[ai][bj][m][n] = __builtin_amdgcn_mfma_f32_16x16x32_bf16(Bt[n][k], At[m][k], acc[ai][bj][m][n], 0, 0, 0); __builtin_amdgcn_s_setprio(0); } while (0)
; #define PG8_WAIT_V(n) asm volatile("s_waitcnt vmcnt(" #n ")" ::: "memory")
; #define PG8_WAIT_L(n) asm volatile("s_waitcnt lgkmcnt(" #n ")" ::: "memory")
; #define PG8_BAR __builtin_amdgcn_s_barrier()
; #define PG8_SCHED __builtin_amdgcn_sched_barrier(0)
; template <class Epi, class Sched, bool ALIGN_EPI = true>
; __device__ __forceinline__ void gemm_phase(LAS unsigned char* lds, const int wave_s, const int K, const Sched& S, const Epi& E) {
;     ...
;             PG8_WAIT_V(8); PG8_WAIT_L(0); PG8_BAR; PG8_MMA(0, 0, At, B0); PG8_MMA(0, 1, At, B1); PG8_BAR; PG8_SCHED;
;             PG8_LDA(At, 0, 1); PG8_STAGE(PG8_SB(0, 0), b2, voffB); PG8_STAGE(PG8_SB(0, 1), b2 + hstep, voffB); PG8_STAGE(PG8_SA(0, 0), a2, voffA);
;             PG8_WAIT_V(8); PG8_WAIT_L(0); PG8_BAR; PG8_MMA(1, 0, At, B0); PG8_MMA(1, 1, At, B1); PG8_BAR; PG8_SCHED;
	s_setprio 1
	s_waitcnt lgkmcnt(0)
	v_mfma_f32_16x16x32_bf16 v[126:129], v[146:149], v[186:189], v[126:129]
	v_mfma_f32_16x16x32_bf16 v[122:125], v[154:157], v[186:189], v[122:125]
	v_mfma_f32_16x16x32_bf16 v[110:113], v[146:149], v[206:209], v[110:113]
	v_mfma_f32_16x16x32_bf16 v[106:109], v[154:157], v[206:209], v[106:109]
	v_mfma_f32_16x16x32_bf16 v[94:97], v[146:149], v[214:217], v[94:97]
	v_mfma_f32_16x16x32_bf16 v[90:93], v[154:157], v[214:217], v[90:93]
	v_mfma_f32_16x16x32_bf16 v[78:81], v[146:149], v[222:225], v[78:81]
	v_mfma_f32_16x16x32_bf16 v[74:77], v[154:157], v[222:225], v[74:77]
	v_mfma_f32_16x16x32_bf16 v[126:129], v[150:153], v[202:205], v[126:129]
	v_mfma_f32_16x16x32_bf16 v[122:125], v[166:169], v[202:205], v[122:125]
	v_mfma_f32_16x16x32_bf16 v[110:113], v[150:153], v[210:213], v[110:113]
	v_mfma_f32_16x16x32_bf16 v[106:109], v[166:169], v[210:213], v[106:109]
	v_mfma_f32_16x16x32_bf16 v[94:97], v[150:153], v[218:221], v[94:97]
	v_mfma_f32_16x16x32_bf16 v[90:93], v[166:169], v[218:221], v[90:93]
	v_mfma_f32_16x16x32_bf16 v[78:81], v[150:153], v[226:229], v[78:81]
	v_mfma_f32_16x16x32_bf16 v[74:77], v[166:169], v[226:229], v[74:77]
	s_setprio 0
	s_setprio 1
	v_mfma_f32_16x16x32_bf16 v[118:121], v[170:173], v[186:189], v[118:121]
	v_mfma_f32_16x16x32_bf16 v[114:117], v[178:181], v[186:189], v[114:117]
	v_mfma_f32_16x16x32_bf16 v[102:105], v[170:173], v[206:209], v[102:105]
	v_mfma_f32_16x16x32_bf16 v[98:101], v[178:181], v[206:209], v[98:101]
	v_mfma_f32_16x16x32_bf16 v[86:89], v[170:173], v[214:217], v[86:89]
	v_mfma_f32_16x16x32_bf16 v[82:85], v[178:181], v[214:217], v[82:85]
	v_mfma_f32_16x16x32_bf16 v[70:73], v[170:173], v[222:225], v[70:73]
	v_mfma_f32_16x16x32_bf16 v[66:69], v[178:181], v[222:225], v[66:69]
	v_mfma_f32_16x16x32_bf16 v[118:121], v[174:177], v[202:205], v[118:121]
	v_mfma_f32_16x16x32_bf16 v[114:117], v[182:185], v[202:205], v[114:117]
	v_mfma_f32_16x16x32_bf16 v[102:105], v[174:177], v[210:213], v[102:105]
	v_mfma_f32_16x16x32_bf16 v[98:101], v[182:185], v[210:213], v[98:101]
	v_mfma_f32_16x16x32_bf16 v[86:89], v[174:177], v[218:221], v[86:89]
	v_mfma_f32_16x16x32_bf16 v[82:85], v[182:185], v[218:221], v[82:85]
	v_mfma_f32_16x16x32_bf16 v[70:73], v[174:177], v[226:229], v[70:73]
	v_mfma_f32_16x16x32_bf16 v[66:69], v[182:185], v[226:229], v[66:69]
	s_setprio 0
	s_barrier
	s_add_i32 s63, s63, s33
	v_lshl_add_u64 v[140:141], s[50:51], 0, v[0:1]
	s_mov_b32 m0, s63
	ds_read_b128 v[186:189], v145 offset:16384
	ds_read_b128 v[202:205], v145 offset:17408
	ds_read_b128 v[206:209], v145 offset:18432
	ds_read_b128 v[210:213], v145 offset:19456
	ds_read_b128 v[214:217], v145 offset:20480
	ds_read_b128 v[218:221], v145 offset:21504
	ds_read_b128 v[222:225], v145 offset:22528
	ds_read_b128 v[226:229], v145 offset:23552
	global_load_lds_dwordx4 v[140:141], off
	s_add_i32 m0, s63, 0x2000
	s_add_u32 s64, s50, 0x40000
	v_lshl_add_u64 v[158:159], s[50:51], 0, v[130:131]
	s_addc_u32 s65, s51, 0
	s_add_i32 s63, s68, s33
	global_load_lds_dwordx4 v[158:159], off
	v_lshl_add_u64 v[160:161], s[64:65], 0, v[0:1]
	s_mov_b32 m0, s63
	v_lshl_add_u64 v[162:163], s[52:53], 0, v[132:133]
	global_load_lds_dwordx4 v[160:161], off
	v_lshl_add_u64 v[160:161], s[64:65], 0, v[130:131]
	s_add_i32 m0, s63, 0x2000
	s_nop 0
	global_load_lds_dwordx4 v[160:161], off
	v_lshl_add_u64 v[160:161], s[52:53], 0, v[134:135]
	s_mov_b32 m0, s18
	s_nop 0
	global_load_lds_dwordx4 v[160:161], off
	s_mov_b32 m0, s19
	s_nop 0
	global_load_lds_dwordx4 v[162:163], off
	s_waitcnt vmcnt(24)
	s_waitcnt lgkmcnt(0)
	s_barrier
	s_setprio 1
	s_waitcnt lgkmcnt(0)
	v_mfma_f32_16x16x32_bf16 v[62:65], v[146:149], v[186:189], v[62:65]
	v_mfma_f32_16x16x32_bf16 v[58:61], v[154:157], v[186:189], v[58:61]
	v_mfma_f32_16x16x32_bf16 v[46:49], v[146:149], v[206:209], v[46:49]
	v_mfma_f32_16x16x32_bf16 v[42:45], v[154:157], v[206:209], v[42:45]
	v_mfma_f32_16x16x32_bf16 v[30:33], v[146:149], v[214:217], v[30:33]
	v_mfma_f32_16x16x32_bf16 v[26:29], v[154:157], v[214:217], v[26:29]
	v_mfma_f32_16x16x32_bf16 v[14:17], v[146:149], v[222:225], v[14:17]
	v_mfma_f32_16x16x32_bf16 v[10:13], v[154:157], v[222:225], v[10:13]
	v_mfma_f32_16x16x32_bf16 v[62:65], v[150:153], v[202:205], v[62:65]
	v_mfma_f32_16x16x32_bf16 v[58:61], v[166:169], v[202:205], v[58:61]
	v_mfma_f32_16x16x32_bf16 v[46:49], v[150:153], v[210:213], v[46:49]
	v_mfma_f32_16x16x32_bf16 v[42:45], v[166:169], v[210:213], v[42:45]
	v_mfma_f32_16x16x32_bf16 v[30:33], v[150:153], v[218:221], v[30:33]
	v_mfma_f32_16x16x32_bf16 v[26:29], v[166:169], v[218:221], v[26:29]
	v_mfma_f32_16x16x32_bf16 v[14:17], v[150:153], v[226:229], v[14:17]
	v_mfma_f32_16x16x32_bf16 v[10:13], v[166:169], v[226:229], v[10:13]
	s_setprio 0
	s_setprio 1
	v_mfma_f32_16x16x32_bf16 v[54:57], v[170:173], v[186:189], v[54:57]
	v_mfma_f32_16x16x32_bf16 v[50:53], v[178:181], v[186:189], v[50:53]
	v_mfma_f32_16x16x32_bf16 v[38:41], v[170:173], v[206:209], v[38:41]
	v_mfma_f32_16x16x32_bf16 v[34:37], v[178:181], v[206:209], v[34:37]
	v_mfma_f32_16x16x32_bf16 v[22:25], v[170:173], v[214:217], v[22:25]
	v_mfma_f32_16x16x32_bf16 v[18:21], v[178:181], v[214:217], v[18:21]
	v_mfma_f32_16x16x32_bf16 v[6:9], v[170:173], v[222:225], v[6:9]
	v_mfma_f32_16x16x32_bf16 v[2:5], v[178:181], v[222:225], v[2:5]
	v_mfma_f32_16x16x32_bf16 v[54:57], v[174:177], v[202:205], v[54:57]
	v_mfma_f32_16x16x32_bf16 v[50:53], v[182:185], v[202:205], v[50:53]
	v_mfma_f32_16x16x32_bf16 v[38:41], v[174:177], v[210:213], v[38:41]
	v_mfma_f32_16x16x32_bf16 v[34:37], v[182:185], v[210:213], v[34:37]
	v_mfma_f32_16x16x32_bf16 v[22:25], v[174:177], v[218:221], v[22:25]
	v_mfma_f32_16x16x32_bf16 v[18:21], v[182:185], v[218:221], v[18:21]
	v_mfma_f32_16x16x32_bf16 v[6:9], v[174:177], v[226:229], v[6:9]
	v_mfma_f32_16x16x32_bf16 v[2:5], v[182:185], v[226:229], v[2:5]
	s_setprio 0
	s_barrier
; #define PG8_STAGE(bufoff, gbase, voff) do { _Pragma("unroll") for (int _i = 0; _i < 2; ++_i) \
;         __builtin_amdgcn_global_load_lds((const unsigned*)((const char*)(gbase) + (voff)[_i]), (LAS unsigned*)(lds + (bufoff) + ldsw + _i * 8192), 16, 0, 0); } while (0)
; #define PG8_LDA(dst, b, h) do { _Pragma("unroll") for (int m = 0; m < 4; ++m) _Pragma("unroll") for (int k = 0; k < 2; ++k) dst[m][k] = *(const LAS bf16x8*)(lds + PG8_SA(b, h) + aoff + m * 2048 + k * 1024); } while (0)
; #define PG8_LDB(dst, b, h) do { _Pragma("unroll") for (int n = 0; n < 2; ++n) _Pragma("unroll") for (int k = 0; k < 2; ++k) dst[n][k] = *(const LAS bf16x8*)(lds + PG8_SB(b, h) + boff + n * 2048 + k * 1024); } while (0)
; #define PG8_MMA(ai, bj, At, Bt) do { __builtin_amdgcn_s_setprio(1); _Pragma("unroll") for (int m = 0; m < 4; ++m) _Pragma("unroll") for (int n = 0; n < 2; ++n) _Pragma("unroll") for (int k = 0; k < 2; ++k) \
;         acc[ai][bj][m][n] = __builtin_amdgcn_mfma_f32_16x16x32_bf16(Bt[n][k], At[m][k], acc[ai][bj][m][n], 0, 0, 0); __builtin_amdgcn_s_setprio(0); } while (0)
; #define PG8_WAIT_V(n) asm volatile("s_waitcnt vmcnt(" #n ")" ::: "memory")
; #define PG8_WAIT_L(n) asm volatile("s_waitcnt lgkmcnt(" #n ")" ::: "memory")
; #define PG8_BAR __builtin_amdgcn_s_barrier()
; #define PG8_SCHED __builtin_amdgcn_sched_barrier(0)
; template <class Epi, class Sched, bool ALIGN_EPI = true>
; __device__ __forceinline__ void gemm_phase(LAS unsigned char* lds, const int wave_s, const int K, const Sched& S, const Epi& E) {
;     ...
;             PG8_LDB(B0, 1, 0); PG8_LDB(B1, 1, 1); PG8_SCHED; PG8_LDA(At, 1, 0); PG8_STAGE(PG8_SA(0, 1), a2 + hstep, voffA);
;             PG8_WAIT_V(8); PG8_WAIT_L(0); PG8_BAR; PG8_MMA(0, 0, At, B0); PG8_MMA(0, 1, At, B1); PG8_BAR; PG8_SCHED;
	s_add_i32 s63, 0, 0x18000
	v_add_u32_e32 v164, s63, v143
	s_add_i32 s64, 0, 0x1c000
	ds_read_b128 v[146:149], v164
	ds_read_b128 v[150:153], v164 offset:1024
	ds_read_b128 v[154:157], v164 offset:2048
	ds_read_b128 v[166:169], v164 offset:3072
	v_add_u32_e32 v164, s64, v143
	ds_read_b128 v[170:173], v164
	ds_read_b128 v[174:177], v164 offset:1024
	ds_read_b128 v[178:181], v164 offset:2048
	ds_read_b128 v[182:185], v164 offset:3072
	s_add_u32 s52, s52, 0x40000
	s_addc_u32 s53, s53, 0
	s_mov_b32 m0, s20
	v_lshl_add_u64 v[164:165], s[52:53], 0, v[134:135]
	ds_read_b128 v[186:189], v145 offset:32768
	ds_read_b128 v[202:205], v145 offset:33792
	ds_read_b128 v[206:209], v145 offset:34816
	ds_read_b128 v[210:213], v145 offset:35840
	ds_read_b128 v[214:217], v145 offset:36864
	ds_read_b128 v[218:221], v145 offset:37888
	ds_read_b128 v[222:225], v145 offset:38912
	ds_read_b128 v[226:229], v145 offset:39936
	global_load_lds_dwordx4 v[164:165], off
	v_lshl_add_u64 v[164:165], s[52:53], 0, v[132:133]
	s_mov_b32 m0, s21
	s_nop 0
	global_load_lds_dwordx4 v[164:165], off
	s_waitcnt vmcnt(24)
	s_waitcnt lgkmcnt(0)
	s_barrier
	s_setprio 1
	s_waitcnt lgkmcnt(0)
	v_mfma_f32_16x16x32_bf16 v[126:129], v[146:149], v[186:189], v[126:129]
	v_mfma_f32_16x16x32_bf16 v[122:125], v[154:157], v[186:189], v[122:125]
	v_mfma_f32_16x16x32_bf16 v[110:113], v[146:149], v[206:209], v[110:113]
	v_mfma_f32_16x16x32_bf16 v[106:109], v[154:157], v[206:209], v[106:109]
	v_mfma_f32_16x16x32_bf16 v[94:97], v[146:149], v[214:217], v[94:97]
	v_mfma_f32_16x16x32_bf16 v[90:93], v[154:157], v[214:217], v[90:93]
	v_mfma_f32_16x16x32_bf16 v[78:81], v[146:149], v[222:225], v[78:81]
	v_mfma_f32_16x16x32_bf16 v[74:77], v[154:157], v[222:225], v[74:77]
	v_mfma_f32_16x16x32_bf16 v[126:129], v[150:153], v[202:205], v[126:129]
	v_mfma_f32_16x16x32_bf16 v[122:125], v[166:169], v[202:205], v[122:125]
	v_mfma_f32_16x16x32_bf16 v[110:113], v[150:153], v[210:213], v[110:113]
	v_mfma_f32_16x16x32_bf16 v[106:109], v[166:169], v[210:213], v[106:109]
	v_mfma_f32_16x16x32_bf16 v[94:97], v[150:153], v[218:221], v[94:97]
	v_mfma_f32_16x16x32_bf16 v[90:93], v[166:169], v[218:221], v[90:93]
	v_mfma_f32_16x16x32_bf16 v[78:81], v[150:153], v[226:229], v[78:81]
	v_mfma_f32_16x16x32_bf16 v[74:77], v[166:169], v[226:229], v[74:77]
	s_setprio 0
	s_setprio 1
	v_mfma_f32_16x16x32_bf16 v[118:121], v[170:173], v[186:189], v[118:121]
	v_mfma_f32_16x16x32_bf16 v[114:117], v[178:181], v[186:189], v[114:117]
	v_mfma_f32_16x16x32_bf16 v[102:105], v[170:173], v[206:209], v[102:105]
	v_mfma_f32_16x16x32_bf16 v[98:101], v[178:181], v[206:209], v[98:101]
	v_mfma_f32_16x16x32_bf16 v[86:89], v[170:173], v[214:217], v[86:89]
	v_mfma_f32_16x16x32_bf16 v[82:85], v[178:181], v[214:217], v[82:85]
	v_mfma_f32_16x16x32_bf16 v[70:73], v[170:173], v[222:225], v[70:73]
	v_mfma_f32_16x16x32_bf16 v[66:69], v[178:181], v[222:225], v[66:69]
	v_mfma_f32_16x16x32_bf16 v[118:121], v[174:177], v[202:205], v[118:121]
	v_mfma_f32_16x16x32_bf16 v[114:117], v[182:185], v[202:205], v[114:117]
	v_mfma_f32_16x16x32_bf16 v[102:105], v[174:177], v[210:213], v[102:105]
	v_mfma_f32_16x16x32_bf16 v[98:101], v[182:185], v[210:213], v[98:101]
	v_mfma_f32_16x16x32_bf16 v[86:89], v[174:177], v[218:221], v[86:89]
	v_mfma_f32_16x16x32_bf16 v[82:85], v[182:185], v[218:221], v[82:85]
	v_mfma_f32_16x16x32_bf16 v[70:73], v[174:177], v[226:229], v[70:73]
	v_mfma_f32_16x16x32_bf16 v[66:69], v[182:185], v[226:229], v[66:69]
	s_setprio 0
	s_barrier
; #define PG8_STAGE(bufoff, gbase, voff) do { _Pragma("unroll") for (int _i = 0; _i < 2; ++_i) \
;         __builtin_amdgcn_global_load_lds((const unsigned*)((const char*)(gbase) + (voff)[_i]), (LAS unsigned*)(lds + (bufoff) + ldsw + _i * 8192), 16, 0, 0); } while (0)
; #define PG8_LDA(dst, b, h) do { _Pragma("unroll") for (int m = 0; m < 4; ++m) _Pragma("unroll") for (int k = 0; k < 2; ++k) dst[m][k] = *(const LAS bf16x8*)(lds + PG8_SA(b, h) + aoff + m * 2048 + k * 1024); } while (0)
; #define PG8_MMA(ai, bj, At, Bt) do { __builtin_amdgcn_s_setprio(1); _Pragma("unroll") for (int m = 0; m < 4; ++m) _Pragma("unroll") for (int n = 0; n < 2; ++n) _Pragma("unroll") for (int k = 0; k < 2; ++k) \
;         acc[ai][bj][m][n] = __builtin_amdgcn_mfma_f32_16x16x32_bf16(Bt[n][k], At[m][k], acc[ai][bj][m][n], 0, 0, 0); __builtin_amdgcn_s_setprio(0); } while (0)
; #define PG8_WAIT_V(n) asm volatile("s_waitcnt vmcnt(" #n ")" ::: "memory")
; #define PG8_WAIT_L(n) asm volatile("s_waitcnt lgkmcnt(" #n ")" ::: "memory")
; #define PG8_BAR __builtin_amdgcn_s_barrier()
; #define PG8_SCHED __builtin_amdgcn_sched_barrier(0)
; template <class Epi, class Sched, bool ALIGN_EPI = true>
; __device__ __forceinline__ void gemm_phase(LAS unsigned char* lds, const int wave_s, const int K, const Sched& S, const Epi& E) {
;     ...
;             PG8_LDA(At, 1, 1); PG8_STAGE(PG8_SB(1, 0), b3, voffB); PG8_STAGE(PG8_SB(1, 1), b3 + hstep, voffB); PG8_STAGE(PG8_SA(1, 0), a3, voffA);
;             PG8_WAIT_V(8); PG8_WAIT_L(0); PG8_BAR; PG8_MMA(1, 0, At, B0); PG8_MMA(1, 1, At, B1); PG8_BAR; PG8_SCHED;
	s_add_i32 s52, s63, s33
	v_lshl_add_u64 v[140:141], v[140:141], 0, s[22:23]
	s_mov_b32 m0, s52
	ds_read_b128 v[186:189], v145 offset:49152
	ds_read_b128 v[202:205], v145 offset:50176
	ds_read_b128 v[206:209], v145 offset:51200
	ds_read_b128 v[210:213], v145 offset:52224
	ds_read_b128 v[214:217], v145 offset:53248
	ds_read_b128 v[218:221], v145 offset:54272
	ds_read_b128 v[222:225], v145 offset:55296
	ds_read_b128 v[226:229], v145 offset:56320
	global_load_lds_dwordx4 v[140:141], off
	s_add_i32 m0, s52, 0x2000
	s_add_u32 s50, s50, 0x40080
	v_lshl_add_u64 v[140:141], v[158:159], 0, s[22:23]
	s_addc_u32 s51, s51, 0
	s_add_i32 s52, s64, s33
	global_load_lds_dwordx4 v[140:141], off
	v_lshl_add_u64 v[140:141], s[50:51], 0, v[0:1]
	s_mov_b32 m0, s52
	s_nop 0
	global_load_lds_dwordx4 v[140:141], off
	v_lshl_add_u64 v[140:141], s[50:51], 0, v[130:131]
	s_add_i32 m0, s52, 0x2000
	s_nop 0
	global_load_lds_dwordx4 v[140:141], off
	v_lshl_add_u64 v[140:141], v[160:161], 0, s[22:23]
	s_mov_b32 m0, s28
	s_nop 0
	global_load_lds_dwordx4 v[140:141], off
	v_lshl_add_u64 v[140:141], v[162:163], 0, s[22:23]
	s_mov_b32 m0, s30
	s_nop 0
	global_load_lds_dwordx4 v[140:141], off
	s_waitcnt vmcnt(24)
	s_waitcnt lgkmcnt(0)
	s_barrier
	s_setprio 1
	s_waitcnt lgkmcnt(0)
	v_mfma_f32_16x16x32_bf16 v[62:65], v[146:149], v[186:189], v[62:65]
	v_mfma_f32_16x16x32_bf16 v[58:61], v[154:157], v[186:189], v[58:61]
	v_mfma_f32_16x16x32_bf16 v[46:49], v[146:149], v[206:209], v[46:49]
	v_mfma_f32_16x16x32_bf16 v[42:45], v[154:157], v[206:209], v[42:45]
	v_mfma_f32_16x16x32_bf16 v[30:33], v[146:149], v[214:217], v[30:33]
	v_mfma_f32_16x16x32_bf16 v[26:29], v[154:157], v[214:217], v[26:29]
	v_mfma_f32_16x16x32_bf16 v[14:17], v[146:149], v[222:225], v[14:17]
	v_mfma_f32_16x16x32_bf16 v[10:13], v[154:157], v[222:225], v[10:13]
	v_mfma_f32_16x16x32_bf16 v[62:65], v[150:153], v[202:205], v[62:65]
	v_mfma_f32_16x16x32_bf16 v[58:61], v[166:169], v[202:205], v[58:61]
	v_mfma_f32_16x16x32_bf16 v[46:49], v[150:153], v[210:213], v[46:49]
	v_mfma_f32_16x16x32_bf16 v[42:45], v[166:169], v[210:213], v[42:45]
	v_mfma_f32_16x16x32_bf16 v[30:33], v[150:153], v[218:221], v[30:33]
	v_mfma_f32_16x16x32_bf16 v[26:29], v[166:169], v[218:221], v[26:29]
	v_mfma_f32_16x16x32_bf16 v[14:17], v[150:153], v[226:229], v[14:17]
	v_mfma_f32_16x16x32_bf16 v[10:13], v[166:169], v[226:229], v[10:13]
	s_setprio 0
	s_setprio 1
	v_mfma_f32_16x16x32_bf16 v[54:57], v[170:173], v[186:189], v[54:57]
	v_mfma_f32_16x16x32_bf16 v[50:53], v[178:181], v[186:189], v[50:53]
	v_mfma_f32_16x16x32_bf16 v[38:41], v[170:173], v[206:209], v[38:41]
	v_mfma_f32_16x16x32_bf16 v[34:37], v[178:181], v[206:209], v[34:37]
	v_mfma_f32_16x16x32_bf16 v[22:25], v[170:173], v[214:217], v[22:25]
	v_mfma_f32_16x16x32_bf16 v[18:21], v[178:181], v[214:217], v[18:21]
	v_mfma_f32_16x16x32_bf16 v[6:9], v[170:173], v[222:225], v[6:9]
	v_mfma_f32_16x16x32_bf16 v[2:5], v[178:181], v[222:225], v[2:5]
	v_mfma_f32_16x16x32_bf16 v[54:57], v[174:177], v[202:205], v[54:57]
	v_mfma_f32_16x16x32_bf16 v[50:53], v[182:185], v[202:205], v[50:53]
	v_mfma_f32_16x16x32_bf16 v[38:41], v[174:177], v[210:213], v[38:41]
	v_mfma_f32_16x16x32_bf16 v[34:37], v[182:185], v[210:213], v[34:37]
	v_mfma_f32_16x16x32_bf16 v[22:25], v[174:177], v[218:221], v[22:25]
	v_mfma_f32_16x16x32_bf16 v[18:21], v[182:185], v[218:221], v[18:21]
	v_mfma_f32_16x16x32_bf16 v[6:9], v[174:177], v[226:229], v[6:9]
	v_mfma_f32_16x16x32_bf16 v[2:5], v[182:185], v[226:229], v[2:5]
	s_setprio 0
	s_barrier
	s_add_i32 s62, s62, 2
	s_add_u32 s48, s48, 0x100
	s_addc_u32 s49, s49, 0
	s_add_u32 s60, s60, 0x100
	s_addc_u32 s61, s61, 0
	s_cmp_gt_u32 s62, 13

; #define PG8_STAGE(bufoff, gbase, voff) do { _Pragma("unroll") for (int _i = 0; _i < 2; ++_i) \
;         __builtin_amdgcn_global_load_lds((const unsigned*)((const char*)(gbase) + (voff)[_i]), (LAS unsigned*)(lds + (bufoff) + ldsw + _i * 8192), 16, 0, 0); } while (0)
; #define PG8_WAIT_V(n) asm volatile("s_waitcnt vmcnt(" #n ")" ::: "memory")
; #define PG8_BAR __builtin_amdgcn_s_barrier()
; template <class Epi, class Sched, bool ALIGN_EPI = true>
; __device__ __forceinline__ void gemm_phase(LAS unsigned char* lds, const int wave_s, const int K, const Sched& S, const Epi& E) {
;     ...
;     PG8_WAIT_V(2); PG8_BAR;
;     PG8_STAGE(PG8_SB(1, 0), cB + kstep, voffB); PG8_STAGE(PG8_SA(1, 0), cA + kstep, voffA); PG8_STAGE(PG8_SB(1, 1), cB + hstep + kstep, voffB);
;     PG8_WAIT_V(6); PG8_BAR;
.LBB0_281:
	s_add_u32 s14, s10, 0x6d00000
	s_addc_u32 s15, s11, 0
	s_add_u32 s34, s10, 0x8d00000
	s_addc_u32 s35, s11, 0
	v_readlane_b32 s18, v254, 60
	s_add_u32 s48, s10, 0xcd00000
	v_readlane_b32 s19, v254, 61
	s_mulk_i32 s18, 0xc00
	s_addc_u32 s49, s11, 0
	s_ashr_i32 s19, s18, 31
	s_lshl_b64 s[18:19], s[18:19], 2
	s_add_u32 s65, s42, s18
	v_and_b32_e32 v17, 15, v16
	v_readlane_b32 s18, v253, 6
	v_bfe_u32 v18, v16, 4, 2
	v_lshlrev_b32_e32 v20, 4, v18
	v_or_b32_e32 v170, s18, v17
	v_lshlrev_b32_e32 v19, 6, v170
	s_movk_i32 s18, 0x3c0
	v_lshlrev_b32_e32 v21, 2, v170
	s_addc_u32 s68, s43, s19
	v_and_or_b32 v19, v19, s18, v20
	v_and_b32_e32 v21, 32, v21
	v_readlane_b32 s18, v253, 7
	v_lshlrev_b32_e32 v16, 2, v16
	v_lshl_add_u64 v[2:3], v[2:3], 0, s[22:23]
	s_add_i32 m0, s7, 0x18000
	v_bitop3_b32 v19, v19, s18, v21 bitop3:0xde
	v_lshl_or_b32 v21, v17, 6, v20
	v_and_b32_e32 v16, 32, v16
	v_readlane_b32 s18, v253, 9
	s_waitcnt vmcnt(2)
	s_barrier
	global_load_lds_dwordx4 v[2:3], off
	v_lshl_add_u64 v[2:3], v[4:5], 0, s[22:23]
	s_add_i32 m0, s7, 0x1a000
	s_add_i32 s69, s7, 0x8000
	s_add_i32 s70, s7, 0xa000
	v_bitop3_b32 v171, v21, s18, v16 bitop3:0xde
	global_load_lds_dwordx4 v[2:3], off
	v_lshl_add_u64 v[2:3], v[6:7], 0, s[22:23]
	s_mov_b32 m0, s69
	s_add_u32 s18, s44, 0x40080
	global_load_lds_dwordx4 v[2:3], off
	v_lshl_add_u64 v[2:3], v[8:9], 0, s[22:23]
	s_mov_b32 m0, s70
	s_addc_u32 s19, s45, 0
	global_load_lds_dwordx4 v[2:3], off
	v_lshl_add_u64 v[2:3], s[18:19], 0, v[0:1]
	s_add_i32 m0, s7, 0x1c000
	v_mov_b32_e32 v149, v1
	global_load_lds_dwordx4 v[2:3], off
	v_lshl_add_u64 v[2:3], s[18:19], 0, v[138:139]
	s_add_i32 m0, s7, 0x1e000
	v_readlane_b32 s18, v253, 22
	global_load_lds_dwordx4 v[2:3], off
	v_lshlrev_b32_e32 v2, 14, v13
	v_and_b32_e32 v2, 0xffff8000, v2
	v_lshl_add_u32 v2, v14, 11, v2
	v_and_b32_e32 v3, 1, v13
	v_lshl_or_b32 v2, v3, 6, v2
	v_lshl_add_u32 v148, v15, 1, v2
	v_lshlrev_b32_e32 v2, 14, v10
	v_and_b32_e32 v2, 0xffff8000, v2
	s_waitcnt vmcnt(6)
	v_or3_b32 v144, v20, s18, v17
	v_readlane_b32 s18, v253, 8
	v_lshl_add_u32 v2, v11, 11, v2
	v_and_b32_e32 v3, 1, v10
	v_ashrrev_i32_e32 v145, 31, v144
	v_lshl_or_b32 v172, v18, 3, s18
	v_lshl_or_b32 v2, v3, 6, v2
	v_readlane_b32 s18, v254, 25
	v_lshl_add_u64 v[146:147], v[144:145], 4, s[14:15]
	v_lshl_add_u32 v150, v12, 1, v2
	v_mov_b32_e32 v151, v1
	s_mov_b32 s21, 0
	v_add_u32_e32 v173, 0, v19
	v_readlane_b32 s28, v254, 22
	s_mov_b32 s20, s18
	s_mov_b32 s71, 0
	s_barrier
	v_readlane_b32 s19, v254, 26
	s_mov_b32 s100, 0
	s_branch .LBB0_284

; #define PG8_BAR __builtin_amdgcn_s_barrier()
; template <class Epi, class Sched, bool ALIGN_EPI = true>
; __device__ __forceinline__ void gemm_phase(LAS unsigned char* lds, const int wave_s, const int K, const Sched& S, const Epi& E) {
;     ...
;         if (!has_next) break;
; #pragma unroll
;         for (int a = 0; a < 2; ++a)
; #pragma unroll
;             for (int b = 0; b < 2; ++b)
; #pragma unroll
;                 for (int m = 0; m < 4; ++m)
; #pragma unroll
;                     for (int n = 0; n < 2; ++n) acc[a][b][m][n] = (f32x4){0.f, 0.f, 0.f, 0.f};
;         cur = nxt; cA = nA; cB = nB; ++ui;
;         if constexpr (ALIGN_EPI) { if (wr == 1) PG8_BAR; }
.LBB0_283:
	s_andn2_b64 vcc, exec, s[12:13]
	s_mov_b32 s21, s76
	s_mov_b32 s28, s52
	s_mov_b32 s20, s50
	s_mov_b64 s[44:45], s[62:63]
	s_mov_b64 s[12:13], s[54:55]
	s_cbranch_vccz .LBB0_405
	s_mov_b32 s100, 1

; #define PG8_STAGE(bufoff, gbase, voff) do { _Pragma("unroll") for (int _i = 0; _i < 2; ++_i) \
;         __builtin_amdgcn_global_load_lds((const unsigned*)((const char*)(gbase) + (voff)[_i]), (LAS unsigned*)(lds + (bufoff) + ldsw + _i * 8192), 16, 0, 0); } while (0)
; #define PG8_LDA(dst, b, h) do { _Pragma("unroll") for (int m = 0; m < 4; ++m) _Pragma("unroll") for (int k = 0; k < 2; ++k) dst[m][k] = *(const LAS bf16x8*)(lds + PG8_SA(b, h) + aoff + m * 2048 + k * 1024); } while (0)
; #define PG8_LDB(dst, b, h) do { _Pragma("unroll") for (int n = 0; n < 2; ++n) _Pragma("unroll") for (int k = 0; k < 2; ++k) dst[n][k] = *(const LAS bf16x8*)(lds + PG8_SB(b, h) + boff + n * 2048 + k * 1024); } while (0)
; #define PG8_MMA(ai, bj, At, Bt) do { __builtin_amdgcn_s_setprio(1); _Pragma("unroll") for (int m = 0; m < 4; ++m) _Pragma("unroll") for (int n = 0; n < 2; ++n) _Pragma("unroll") for (int k = 0; k < 2; ++k) \
;         acc[ai][bj][m][n] = __builtin_amdgcn_mfma_f32_16x16x32_bf16(Bt[n][k], At[m][k], acc[ai][bj][m][n], 0, 0, 0); __builtin_amdgcn_s_setprio(0); } while (0)
; #define PG8_WAIT_V(n) asm volatile("s_waitcnt vmcnt(" #n ")" ::: "memory")
; #define PG8_WAIT_L(n) asm volatile("s_waitcnt lgkmcnt(" #n ")" ::: "memory")
; #define PG8_BAR __builtin_amdgcn_s_barrier()
; #define PG8_SCHED __builtin_amdgcn_sched_barrier(0)
; template <class Epi, class Sched, bool ALIGN_EPI = true>
; __device__ __forceinline__ void gemm_phase(LAS unsigned char* lds, const int wave_s, const int K, const Sched& S, const Epi& E) {
;     ...
;             PG8_LDB(B0, 0, 0); PG8_LDB(B1, 0, 1); PG8_SCHED; PG8_LDA(At, 0, 0); PG8_STAGE(PG8_SA(1, 1), a1 + hstep, voffA);
;             PG8_WAIT_V(8); PG8_WAIT_L(0); PG8_BAR; PG8_MMA(0, 0, At, B0); PG8_MMA(0, 1, At, B1); PG8_BAR; PG8_SCHED;
;     ...
; #pragma unroll
;         for (int a = 0; a < 2; ++a)
; #pragma unroll
;             for (int b = 0; b < 2; ++b)
; #pragma unroll
;                 for (int m = 0; m < 4; ++m)
; #pragma unroll
;                     for (int n = 0; n < 2; ++n) acc[a][b][m][n] = (f32x4){0.f, 0.f, 0.f, 0.f};
;         cur = nxt; cA = nA; cB = nB; ++ui;
.LBB0_298:
	s_add_u32 s12, s12, 0x40080
	s_addc_u32 s13, s13, 0
	s_add_u32 s18, s44, 0x100
	v_mov_b32_e32 v2, 0
	s_addc_u32 s19, s45, 0
	s_mov_b32 s30, -2
	v_mov_b32_e32 v3, v2
	v_mov_b32_e32 v4, v2
	v_mov_b32_e32 v5, v2
	v_mov_b32_e32 v6, v2
	v_mov_b32_e32 v7, v2
	v_mov_b32_e32 v8, v2
	v_mov_b32_e32 v9, v2
	v_mov_b32_e32 v10, v2
	v_mov_b32_e32 v11, v2
	v_mov_b32_e32 v12, v2
	v_mov_b32_e32 v13, v2
	v_mov_b32_e32 v14, v2
	v_mov_b32_e32 v15, v2
	v_mov_b32_e32 v16, v2
	v_mov_b32_e32 v17, v2
	v_mov_b32_e32 v18, v2
	v_mov_b32_e32 v19, v2
	v_mov_b32_e32 v20, v2
	v_mov_b32_e32 v21, v2
	v_mov_b32_e32 v22, v2
	v_mov_b32_e32 v23, v2
	v_mov_b32_e32 v24, v2
	v_mov_b32_e32 v25, v2
	v_mov_b32_e32 v26, v2
	v_mov_b32_e32 v27, v2
	v_mov_b32_e32 v28, v2
	v_mov_b32_e32 v29, v2
	v_mov_b32_e32 v30, v2
	v_mov_b32_e32 v31, v2
	v_mov_b32_e32 v32, v2
	v_mov_b32_e32 v33, v2
	v_mov_b32_e32 v66, v2
	v_mov_b32_e32 v67, v2
	v_mov_b32_e32 v68, v2
	v_mov_b32_e32 v69, v2
	v_mov_b32_e32 v70, v2
	v_mov_b32_e32 v71, v2
	v_mov_b32_e32 v72, v2
	v_mov_b32_e32 v73, v2
	v_mov_b32_e32 v74, v2
	v_mov_b32_e32 v75, v2
	v_mov_b32_e32 v76, v2
	v_mov_b32_e32 v77, v2
	v_mov_b32_e32 v78, v2
	v_mov_b32_e32 v79, v2
	v_mov_b32_e32 v80, v2
	v_mov_b32_e32 v81, v2
	v_mov_b32_e32 v82, v2
	v_mov_b32_e32 v83, v2
	v_mov_b32_e32 v84, v2
	v_mov_b32_e32 v85, v2
	v_mov_b32_e32 v86, v2
	v_mov_b32_e32 v87, v2
	v_mov_b32_e32 v88, v2
	v_mov_b32_e32 v89, v2
	v_mov_b32_e32 v90, v2
	v_mov_b32_e32 v91, v2
	v_mov_b32_e32 v92, v2
	v_mov_b32_e32 v93, v2
	v_mov_b32_e32 v94, v2
	v_mov_b32_e32 v95, v2
	v_mov_b32_e32 v96, v2
	v_mov_b32_e32 v97, v2
	v_mov_b32_e32 v34, v2
	v_mov_b32_e32 v35, v2
	v_mov_b32_e32 v36, v2
	v_mov_b32_e32 v37, v2
	v_mov_b32_e32 v38, v2
	v_mov_b32_e32 v39, v2
	v_mov_b32_e32 v40, v2
	v_mov_b32_e32 v41, v2
	v_mov_b32_e32 v42, v2
	v_mov_b32_e32 v43, v2
	v_mov_b32_e32 v44, v2
	v_mov_b32_e32 v45, v2
	v_mov_b32_e32 v46, v2
	v_mov_b32_e32 v47, v2
	v_mov_b32_e32 v48, v2
	v_mov_b32_e32 v49, v2
	v_mov_b32_e32 v50, v2
	v_mov_b32_e32 v51, v2
	v_mov_b32_e32 v52, v2
	v_mov_b32_e32 v53, v2
	v_mov_b32_e32 v54, v2
	v_mov_b32_e32 v55, v2
	v_mov_b32_e32 v56, v2
	v_mov_b32_e32 v57, v2
	v_mov_b32_e32 v58, v2
	v_mov_b32_e32 v59, v2
	v_mov_b32_e32 v60, v2
	v_mov_b32_e32 v61, v2
	v_mov_b32_e32 v62, v2
	v_mov_b32_e32 v63, v2
	v_mov_b32_e32 v64, v2
	v_mov_b32_e32 v65, v2
	v_mov_b32_e32 v98, v2
	v_mov_b32_e32 v99, v2
	v_mov_b32_e32 v100, v2
	v_mov_b32_e32 v101, v2
	v_mov_b32_e32 v102, v2
	v_mov_b32_e32 v103, v2
	v_mov_b32_e32 v104, v2
	v_mov_b32_e32 v105, v2
	v_mov_b32_e32 v106, v2
	v_mov_b32_e32 v107, v2
	v_mov_b32_e32 v108, v2
	v_mov_b32_e32 v109, v2
	v_mov_b32_e32 v110, v2
	v_mov_b32_e32 v111, v2
	v_mov_b32_e32 v112, v2
	v_mov_b32_e32 v113, v2
	v_mov_b32_e32 v114, v2
	v_mov_b32_e32 v115, v2
	v_mov_b32_e32 v116, v2
	v_mov_b32_e32 v117, v2
	v_mov_b32_e32 v118, v2
	v_mov_b32_e32 v119, v2
	v_mov_b32_e32 v120, v2
	v_mov_b32_e32 v121, v2
	v_mov_b32_e32 v122, v2
	v_mov_b32_e32 v123, v2
	v_mov_b32_e32 v124, v2
	v_mov_b32_e32 v125, v2
	v_mov_b32_e32 v126, v2
	v_mov_b32_e32 v127, v2
	v_mov_b32_e32 v128, v2
	v_mov_b32_e32 v129, v2
	s_cmp_eq_u32 s100, 0
	s_cbranch_scc1 .LBB0_299
	s_add_u32 s36, s12, 0xfffc0080
	s_addc_u32 s44, s13, -1
	s_add_i32 s51, 0, 0x10000
	s_cmp_eq_u32 s30, 12
	s_cselect_b32 s47, s55, s44
	s_cselect_b32 s46, s54, s36
	s_cselect_b32 s45, s63, s19
	s_cselect_b32 s44, s62, s18
	s_add_i32 s36, 0, 0x14000
	v_add_u32_e32 v156, s51, v171
	v_add_u32_e32 v160, s36, v171
	ds_read_b128 v[130:133], v156
	ds_read_b128 v[134:137], v156 offset:1024
	ds_read_b128 v[152:155], v156 offset:2048
	ds_read_b128 v[156:159], v156 offset:3072
	ds_read_b128 v[166:169], v160
	ds_read_b128 v[174:177], v160 offset:1024
	ds_read_b128 v[178:181], v160 offset:2048
	ds_read_b128 v[182:185], v160 offset:3072
	v_lshl_add_u64 v[160:161], s[12:13], 0, v[148:149]
	s_add_i32 m0, s7, 0xc000
	ds_read_b128 v[186:189], v173
	ds_read_b128 v[202:205], v173 offset:1024
	ds_read_b128 v[206:209], v173 offset:2048
	ds_read_b128 v[210:213], v173 offset:3072
	ds_read_b128 v[214:217], v173 offset:4096
	ds_read_b128 v[218:221], v173 offset:5120
	ds_read_b128 v[222:225], v173 offset:6144
	ds_read_b128 v[226:229], v173 offset:7168
	global_load_lds_dwordx4 v[160:161], off
	v_lshl_add_u64 v[160:161], s[12:13], 0, v[150:151]
	s_add_i32 m0, s7, 0xe000
	s_nop 0
	global_load_lds_dwordx4 v[160:161], off
	s_waitcnt vmcnt(16)
	s_waitcnt lgkmcnt(0)
	s_barrier
	s_setprio 1
	s_waitcnt lgkmcnt(0)
	v_mfma_f32_16x16x32_bf16 v[126:129], v[130:133], v[186:189], v[126:129]
	v_mfma_f32_16x16x32_bf16 v[122:125], v[152:155], v[186:189], v[122:125]
	v_mfma_f32_16x16x32_bf16 v[118:121], v[130:133], v[206:209], v[118:121]
	v_mfma_f32_16x16x32_bf16 v[114:117], v[152:155], v[206:209], v[114:117]
	v_mfma_f32_16x16x32_bf16 v[110:113], v[130:133], v[214:217], v[110:113]
	v_mfma_f32_16x16x32_bf16 v[106:109], v[152:155], v[214:217], v[106:109]
	v_mfma_f32_16x16x32_bf16 v[102:105], v[130:133], v[222:225], v[102:105]
	v_mfma_f32_16x16x32_bf16 v[98:101], v[152:155], v[222:225], v[98:101]
	v_mfma_f32_16x16x32_bf16 v[126:129], v[134:137], v[202:205], v[126:129]
	v_mfma_f32_16x16x32_bf16 v[122:125], v[156:159], v[202:205], v[122:125]
	v_mfma_f32_16x16x32_bf16 v[118:121], v[134:137], v[210:213], v[118:121]
	v_mfma_f32_16x16x32_bf16 v[114:117], v[156:159], v[210:213], v[114:117]
	v_mfma_f32_16x16x32_bf16 v[110:113], v[134:137], v[218:221], v[110:113]
	v_mfma_f32_16x16x32_bf16 v[106:109], v[156:159], v[218:221], v[106:109]
	v_mfma_f32_16x16x32_bf16 v[102:105], v[134:137], v[226:229], v[102:105]
	v_mfma_f32_16x16x32_bf16 v[98:101], v[156:159], v[226:229], v[98:101]
	s_setprio 0
	s_setprio 1
	v_mfma_f32_16x16x32_bf16 v[62:65], v[166:169], v[186:189], v[62:65]
	v_mfma_f32_16x16x32_bf16 v[58:61], v[178:181], v[186:189], v[58:61]
	v_mfma_f32_16x16x32_bf16 v[54:57], v[166:169], v[206:209], v[54:57]
	v_mfma_f32_16x16x32_bf16 v[50:53], v[178:181], v[206:209], v[50:53]
	v_mfma_f32_16x16x32_bf16 v[46:49], v[166:169], v[214:217], v[46:49]
	v_mfma_f32_16x16x32_bf16 v[42:45], v[178:181], v[214:217], v[42:45]
	v_mfma_f32_16x16x32_bf16 v[38:41], v[166:169], v[222:225], v[38:41]
	v_mfma_f32_16x16x32_bf16 v[34:37], v[178:181], v[222:225], v[34:37]
	v_mfma_f32_16x16x32_bf16 v[62:65], v[174:177], v[202:205], v[62:65]
	v_mfma_f32_16x16x32_bf16 v[58:61], v[182:185], v[202:205], v[58:61]
	v_mfma_f32_16x16x32_bf16 v[54:57], v[174:177], v[210:213], v[54:57]
	v_mfma_f32_16x16x32_bf16 v[50:53], v[182:185], v[210:213], v[50:53]
	v_mfma_f32_16x16x32_bf16 v[46:49], v[174:177], v[218:221], v[46:49]
	v_mfma_f32_16x16x32_bf16 v[42:45], v[182:185], v[218:221], v[42:45]
	v_mfma_f32_16x16x32_bf16 v[38:41], v[174:177], v[226:229], v[38:41]
	v_mfma_f32_16x16x32_bf16 v[34:37], v[182:185], v[226:229], v[34:37]
	s_setprio 0
	s_barrier
; #define PG8_STAGE(bufoff, gbase, voff) do { _Pragma("unroll") for (int _i = 0; _i < 2; ++_i) \
;         __builtin_amdgcn_global_load_lds((const unsigned*)((const char*)(gbase) + (voff)[_i]), (LAS unsigned*)(lds + (bufoff) + ldsw + _i * 8192), 16, 0, 0); } while (0)
; #define PG8_LDA(dst, b, h) do { _Pragma("unroll") for (int m = 0; m < 4; ++m) _Pragma("unroll") for (int k = 0; k < 2; ++k) dst[m][k] = *(const LAS bf16x8*)(lds + PG8_SA(b, h) + aoff + m * 2048 + k * 1024); } while (0)
; #define PG8_LDB(dst, b, h) do { _Pragma("unroll") for (int n = 0; n < 2; ++n) _Pragma("unroll") for (int k = 0; k < 2; ++k) dst[n][k] = *(const LAS bf16x8*)(lds + PG8_SB(b, h) + boff + n * 2048 + k * 1024); } while (0)
; #define PG8_MMA(ai, bj, At, Bt) do { __builtin_amdgcn_s_setprio(1); _Pragma("unroll") for (int m = 0; m < 4; ++m) _Pragma("unroll") for (int n = 0; n < 2; ++n) _Pragma("unroll") for (int k = 0; k < 2; ++k) \
;         acc[ai][bj][m][n] = __builtin_amdgcn_mfma_f32_16x16x32_bf16(Bt[n][k], At[m][k], acc[ai][bj][m][n], 0, 0, 0); __builtin_amdgcn_s_setprio(0); } while (0)
; #define PG8_WAIT_V(n) asm volatile("s_waitcnt vmcnt(" #n ")" ::: "memory")
; #define PG8_WAIT_L(n) asm volatile("s_waitcnt lgkmcnt(" #n ")" ::: "memory")
; #define PG8_BAR __builtin_amdgcn_s_barrier()
; #define PG8_SCHED __builtin_amdgcn_sched_barrier(0)
; template <class Epi, class Sched, bool ALIGN_EPI = true>
; __device__ __forceinline__ void gemm_phase(LAS unsigned char* lds, const int wave_s, const int K, const Sched& S, const Epi& E) {
;     ...
;             PG8_LDA(At, 0, 1); PG8_STAGE(PG8_SB(0, 0), b2, voffB); PG8_STAGE(PG8_SB(0, 1), b2 + hstep, voffB); PG8_STAGE(PG8_SA(0, 0), a2, voffA);
;             PG8_WAIT_V(8); PG8_WAIT_L(0); PG8_BAR; PG8_MMA(1, 0, At, B0); PG8_MMA(1, 1, At, B1); PG8_BAR; PG8_SCHED;
;             PG8_LDB(B0, 1, 0); PG8_LDB(B1, 1, 1); PG8_SCHED; PG8_LDA(At, 1, 0); PG8_STAGE(PG8_SA(0, 1), a2 + hstep, voffA);
;             PG8_WAIT_V(8); PG8_WAIT_L(0); PG8_BAR; PG8_MMA(0, 0, At, B0); PG8_MMA(0, 1, At, B1); PG8_BAR; PG8_SCHED;
	s_add_i32 s51, s51, s33
	v_lshl_add_u64 v[160:161], s[44:45], 0, v[0:1]
	s_mov_b32 m0, s51
	ds_read_b128 v[186:189], v173 offset:16384
	ds_read_b128 v[202:205], v173 offset:17408
	ds_read_b128 v[206:209], v173 offset:18432
	ds_read_b128 v[210:213], v173 offset:19456
	ds_read_b128 v[214:217], v173 offset:20480
	ds_read_b128 v[218:221], v173 offset:21504
	ds_read_b128 v[222:225], v173 offset:22528
	ds_read_b128 v[226:229], v173 offset:23552
	global_load_lds_dwordx4 v[160:161], off
	s_add_i32 m0, s51, 0x2000
	s_add_u32 s56, s44, 0x40000
	v_lshl_add_u64 v[162:163], s[44:45], 0, v[138:139]
	s_addc_u32 s57, s45, 0
	s_add_i32 s36, s36, s33
	global_load_lds_dwordx4 v[162:163], off
	v_lshl_add_u64 v[164:165], s[56:57], 0, v[0:1]
	s_mov_b32 m0, s36
	v_lshl_add_u64 v[190:191], s[46:47], 0, v[140:141]
	global_load_lds_dwordx4 v[164:165], off
	v_lshl_add_u64 v[164:165], s[56:57], 0, v[138:139]
	s_add_i32 m0, s36, 0x2000
	s_nop 0
	global_load_lds_dwordx4 v[164:165], off
	v_lshl_add_u64 v[164:165], s[46:47], 0, v[142:143]
	s_mov_b32 m0, s7
	s_nop 0
	global_load_lds_dwordx4 v[164:165], off
	s_mov_b32 m0, s16
	s_nop 0
	global_load_lds_dwordx4 v[190:191], off
	s_waitcnt vmcnt(16)
	s_waitcnt lgkmcnt(0)
	s_barrier
	s_setprio 1
	s_waitcnt lgkmcnt(0)
	v_mfma_f32_16x16x32_bf16 v[94:97], v[130:133], v[186:189], v[94:97]
	v_mfma_f32_16x16x32_bf16 v[90:93], v[152:155], v[186:189], v[90:93]
	v_mfma_f32_16x16x32_bf16 v[86:89], v[130:133], v[206:209], v[86:89]
	v_mfma_f32_16x16x32_bf16 v[82:85], v[152:155], v[206:209], v[82:85]
	v_mfma_f32_16x16x32_bf16 v[78:81], v[130:133], v[214:217], v[78:81]
	v_mfma_f32_16x16x32_bf16 v[74:77], v[152:155], v[214:217], v[74:77]
	v_mfma_f32_16x16x32_bf16 v[70:73], v[130:133], v[222:225], v[70:73]
	v_mfma_f32_16x16x32_bf16 v[66:69], v[152:155], v[222:225], v[66:69]
	v_mfma_f32_16x16x32_bf16 v[94:97], v[134:137], v[202:205], v[94:97]
	v_mfma_f32_16x16x32_bf16 v[90:93], v[156:159], v[202:205], v[90:93]
	v_mfma_f32_16x16x32_bf16 v[86:89], v[134:137], v[210:213], v[86:89]
	v_mfma_f32_16x16x32_bf16 v[82:85], v[156:159], v[210:213], v[82:85]
	v_mfma_f32_16x16x32_bf16 v[78:81], v[134:137], v[218:221], v[78:81]
	v_mfma_f32_16x16x32_bf16 v[74:77], v[156:159], v[218:221], v[74:77]
	v_mfma_f32_16x16x32_bf16 v[70:73], v[134:137], v[226:229], v[70:73]
	v_mfma_f32_16x16x32_bf16 v[66:69], v[156:159], v[226:229], v[66:69]
	s_setprio 0
	s_setprio 1
	v_mfma_f32_16x16x32_bf16 v[30:33], v[166:169], v[186:189], v[30:33]
	v_mfma_f32_16x16x32_bf16 v[26:29], v[178:181], v[186:189], v[26:29]
	v_mfma_f32_16x16x32_bf16 v[22:25], v[166:169], v[206:209], v[22:25]
	v_mfma_f32_16x16x32_bf16 v[18:21], v[178:181], v[206:209], v[18:21]
	v_mfma_f32_16x16x32_bf16 v[14:17], v[166:169], v[214:217], v[14:17]
	v_mfma_f32_16x16x32_bf16 v[10:13], v[178:181], v[214:217], v[10:13]
	v_mfma_f32_16x16x32_bf16 v[6:9], v[166:169], v[222:225], v[6:9]
	v_mfma_f32_16x16x32_bf16 v[2:5], v[178:181], v[222:225], v[2:5]
	v_mfma_f32_16x16x32_bf16 v[30:33], v[174:177], v[202:205], v[30:33]
	v_mfma_f32_16x16x32_bf16 v[26:29], v[182:185], v[202:205], v[26:29]
	v_mfma_f32_16x16x32_bf16 v[22:25], v[174:177], v[210:213], v[22:25]
	v_mfma_f32_16x16x32_bf16 v[18:21], v[182:185], v[210:213], v[18:21]
	v_mfma_f32_16x16x32_bf16 v[14:17], v[174:177], v[218:221], v[14:17]
	v_mfma_f32_16x16x32_bf16 v[10:13], v[182:185], v[218:221], v[10:13]
	v_mfma_f32_16x16x32_bf16 v[6:9], v[174:177], v[226:229], v[6:9]
	v_mfma_f32_16x16x32_bf16 v[2:5], v[182:185], v[226:229], v[2:5]
	s_setprio 0
	s_barrier
	s_add_i32 s36, 0, 0x18000
	s_add_i32 s51, 0, 0x1c000
	v_add_u32_e32 v156, s36, v171
	v_add_u32_e32 v182, s51, v171
	ds_read_b128 v[130:133], v156
	ds_read_b128 v[134:137], v156 offset:1024
	ds_read_b128 v[152:155], v156 offset:2048
	ds_read_b128 v[156:159], v156 offset:3072
	ds_read_b128 v[166:169], v182
	ds_read_b128 v[174:177], v182 offset:1024
	ds_read_b128 v[178:181], v182 offset:2048
	ds_read_b128 v[182:185], v182 offset:3072
	s_add_u32 s46, s46, 0x40000
	s_addc_u32 s47, s47, 0
	s_mov_b32 m0, s39
	v_lshl_add_u64 v[196:197], s[46:47], 0, v[142:143]
	ds_read_b128 v[186:189], v173 offset:32768
	ds_read_b128 v[202:205], v173 offset:33792
	ds_read_b128 v[206:209], v173 offset:34816
	ds_read_b128 v[210:213], v173 offset:35840
	ds_read_b128 v[214:217], v173 offset:36864
	ds_read_b128 v[218:221], v173 offset:37888
	ds_read_b128 v[222:225], v173 offset:38912
	ds_read_b128 v[226:229], v173 offset:39936
	global_load_lds_dwordx4 v[196:197], off
	v_lshl_add_u64 v[196:197], s[46:47], 0, v[140:141]
	s_mov_b32 m0, s64
	s_nop 0
	global_load_lds_dwordx4 v[196:197], off
	s_waitcnt vmcnt(16)
	s_waitcnt lgkmcnt(0)
	s_barrier
; #define PG8_STAGE(bufoff, gbase, voff) do { _Pragma("unroll") for (int _i = 0; _i < 2; ++_i) \
;         __builtin_amdgcn_global_load_lds((const unsigned*)((const char*)(gbase) + (voff)[_i]), (LAS unsigned*)(lds + (bufoff) + ldsw + _i * 8192), 16, 0, 0); } while (0)
; #define PG8_LDA(dst, b, h) do { _Pragma("unroll") for (int m = 0; m < 4; ++m) _Pragma("unroll") for (int k = 0; k < 2; ++k) dst[m][k] = *(const LAS bf16x8*)(lds + PG8_SA(b, h) + aoff + m * 2048 + k * 1024); } while (0)
; #define PG8_MMA(ai, bj, At, Bt) do { __builtin_amdgcn_s_setprio(1); _Pragma("unroll") for (int m = 0; m < 4; ++m) _Pragma("unroll") for (int n = 0; n < 2; ++n) _Pragma("unroll") for (int k = 0; k < 2; ++k) \
;         acc[ai][bj][m][n] = __builtin_amdgcn_mfma_f32_16x16x32_bf16(Bt[n][k], At[m][k], acc[ai][bj][m][n], 0, 0, 0); __builtin_amdgcn_s_setprio(0); } while (0)
; #define PG8_WAIT_V(n) asm volatile("s_waitcnt vmcnt(" #n ")" ::: "memory")
; #define PG8_WAIT_L(n) asm volatile("s_waitcnt lgkmcnt(" #n ")" ::: "memory")
; #define PG8_BAR __builtin_amdgcn_s_barrier()
; #define PG8_SCHED __builtin_amdgcn_sched_barrier(0)
; template <class Epi, class Sched, bool ALIGN_EPI = true>
; __device__ __forceinline__ void gemm_phase(LAS unsigned char* lds, const int wave_s, const int K, const Sched& S, const Epi& E) {
;     ...
;             PG8_WAIT_V(8); PG8_WAIT_L(0); PG8_BAR; PG8_MMA(0, 0, At, B0); PG8_MMA(0, 1, At, B1); PG8_BAR; PG8_SCHED;
;             PG8_LDA(At, 1, 1); PG8_STAGE(PG8_SB(1, 0), b3, voffB); PG8_STAGE(PG8_SB(1, 1), b3 + hstep, voffB); PG8_STAGE(PG8_SA(1, 0), a3, voffA);
;             PG8_WAIT_V(8); PG8_WAIT_L(0); PG8_BAR; PG8_MMA(1, 0, At, B0); PG8_MMA(1, 1, At, B1); PG8_BAR; PG8_SCHED;
	s_setprio 1
	s_waitcnt lgkmcnt(0)
	v_mfma_f32_16x16x32_bf16 v[126:129], v[130:133], v[186:189], v[126:129]
	v_mfma_f32_16x16x32_bf16 v[122:125], v[152:155], v[186:189], v[122:125]
	v_mfma_f32_16x16x32_bf16 v[118:121], v[130:133], v[206:209], v[118:121]
	v_mfma_f32_16x16x32_bf16 v[114:117], v[152:155], v[206:209], v[114:117]
	v_mfma_f32_16x16x32_bf16 v[110:113], v[130:133], v[214:217], v[110:113]
	v_mfma_f32_16x16x32_bf16 v[106:109], v[152:155], v[214:217], v[106:109]
	v_mfma_f32_16x16x32_bf16 v[102:105], v[130:133], v[222:225], v[102:105]
	v_mfma_f32_16x16x32_bf16 v[98:101], v[152:155], v[222:225], v[98:101]
	v_mfma_f32_16x16x32_bf16 v[126:129], v[134:137], v[202:205], v[126:129]
	v_mfma_f32_16x16x32_bf16 v[122:125], v[156:159], v[202:205], v[122:125]
	v_mfma_f32_16x16x32_bf16 v[118:121], v[134:137], v[210:213], v[118:121]
	v_mfma_f32_16x16x32_bf16 v[114:117], v[156:159], v[210:213], v[114:117]
	v_mfma_f32_16x16x32_bf16 v[110:113], v[134:137], v[218:221], v[110:113]
	v_mfma_f32_16x16x32_bf16 v[106:109], v[156:159], v[218:221], v[106:109]
	v_mfma_f32_16x16x32_bf16 v[102:105], v[134:137], v[226:229], v[102:105]
	v_mfma_f32_16x16x32_bf16 v[98:101], v[156:159], v[226:229], v[98:101]
	s_setprio 0
	s_setprio 1
	v_mfma_f32_16x16x32_bf16 v[62:65], v[166:169], v[186:189], v[62:65]
	v_mfma_f32_16x16x32_bf16 v[58:61], v[178:181], v[186:189], v[58:61]
	v_mfma_f32_16x16x32_bf16 v[54:57], v[166:169], v[206:209], v[54:57]
	v_mfma_f32_16x16x32_bf16 v[50:53], v[178:181], v[206:209], v[50:53]
	v_mfma_f32_16x16x32_bf16 v[46:49], v[166:169], v[214:217], v[46:49]
	v_mfma_f32_16x16x32_bf16 v[42:45], v[178:181], v[214:217], v[42:45]
	v_mfma_f32_16x16x32_bf16 v[38:41], v[166:169], v[222:225], v[38:41]
	v_mfma_f32_16x16x32_bf16 v[34:37], v[178:181], v[222:225], v[34:37]
	v_mfma_f32_16x16x32_bf16 v[62:65], v[174:177], v[202:205], v[62:65]
	v_mfma_f32_16x16x32_bf16 v[58:61], v[182:185], v[202:205], v[58:61]
	v_mfma_f32_16x16x32_bf16 v[54:57], v[174:177], v[210:213], v[54:57]
	v_mfma_f32_16x16x32_bf16 v[50:53], v[182:185], v[210:213], v[50:53]
	v_mfma_f32_16x16x32_bf16 v[46:49], v[174:177], v[218:221], v[46:49]
	v_mfma_f32_16x16x32_bf16 v[42:45], v[182:185], v[218:221], v[42:45]
	v_mfma_f32_16x16x32_bf16 v[38:41], v[174:177], v[226:229], v[38:41]
	v_mfma_f32_16x16x32_bf16 v[34:37], v[182:185], v[226:229], v[34:37]
	s_setprio 0
	s_barrier
	s_add_i32 s36, s36, s33
	v_lshl_add_u64 v[160:161], v[160:161], 0, s[22:23]
	s_mov_b32 m0, s36
	ds_read_b128 v[186:189], v173 offset:49152
	ds_read_b128 v[202:205], v173 offset:50176
	ds_read_b128 v[206:209], v173 offset:51200
	ds_read_b128 v[210:213], v173 offset:52224
	ds_read_b128 v[214:217], v173 offset:53248
	ds_read_b128 v[218:221], v173 offset:54272
	ds_read_b128 v[222:225], v173 offset:55296
	ds_read_b128 v[226:229], v173 offset:56320
	global_load_lds_dwordx4 v[160:161], off
	s_add_i32 m0, s36, 0x2000
	s_add_u32 s44, s44, 0x40080
	v_lshl_add_u64 v[160:161], v[162:163], 0, s[22:23]
	s_addc_u32 s45, s45, 0
	s_add_i32 s36, s51, s33
	global_load_lds_dwordx4 v[160:161], off
	v_lshl_add_u64 v[160:161], s[44:45], 0, v[0:1]
	s_mov_b32 m0, s36
	s_nop 0
	global_load_lds_dwordx4 v[160:161], off
	v_lshl_add_u64 v[160:161], s[44:45], 0, v[138:139]
	s_add_i32 m0, s36, 0x2000
	s_nop 0
	global_load_lds_dwordx4 v[160:161], off
	v_lshl_add_u64 v[160:161], v[164:165], 0, s[22:23]
	s_mov_b32 m0, s69
	s_nop 0
	global_load_lds_dwordx4 v[160:161], off
	v_lshl_add_u64 v[160:161], v[190:191], 0, s[22:23]
	s_mov_b32 m0, s70
	s_nop 0
	global_load_lds_dwordx4 v[160:161], off
	s_waitcnt vmcnt(16)
	s_waitcnt lgkmcnt(0)
	s_barrier
	s_setprio 1
	s_waitcnt lgkmcnt(0)
	v_mfma_f32_16x16x32_bf16 v[94:97], v[130:133], v[186:189], v[94:97]
	v_mfma_f32_16x16x32_bf16 v[90:93], v[152:155], v[186:189], v[90:93]
	v_mfma_f32_16x16x32_bf16 v[86:89], v[130:133], v[206:209], v[86:89]
	v_mfma_f32_16x16x32_bf16 v[82:85], v[152:155], v[206:209], v[82:85]
	v_mfma_f32_16x16x32_bf16 v[78:81], v[130:133], v[214:217], v[78:81]
	v_mfma_f32_16x16x32_bf16 v[74:77], v[152:155], v[214:217], v[74:77]
	v_mfma_f32_16x16x32_bf16 v[70:73], v[130:133], v[222:225], v[70:73]
	v_mfma_f32_16x16x32_bf16 v[66:69], v[152:155], v[222:225], v[66:69]
	v_mfma_f32_16x16x32_bf16 v[94:97], v[134:137], v[202:205], v[94:97]
	v_mfma_f32_16x16x32_bf16 v[90:93], v[156:159], v[202:205], v[90:93]
	v_mfma_f32_16x16x32_bf16 v[86:89], v[134:137], v[210:213], v[86:89]
	v_mfma_f32_16x16x32_bf16 v[82:85], v[156:159], v[210:213], v[82:85]
	v_mfma_f32_16x16x32_bf16 v[78:81], v[134:137], v[218:221], v[78:81]
	v_mfma_f32_16x16x32_bf16 v[74:77], v[156:159], v[218:221], v[74:77]
	v_mfma_f32_16x16x32_bf16 v[70:73], v[134:137], v[226:229], v[70:73]
	v_mfma_f32_16x16x32_bf16 v[66:69], v[156:159], v[226:229], v[66:69]
	s_setprio 0
	s_setprio 1
	v_mfma_f32_16x16x32_bf16 v[30:33], v[166:169], v[186:189], v[30:33]
	v_mfma_f32_16x16x32_bf16 v[26:29], v[178:181], v[186:189], v[26:29]
	v_mfma_f32_16x16x32_bf16 v[22:25], v[166:169], v[206:209], v[22:25]
	v_mfma_f32_16x16x32_bf16 v[18:21], v[178:181], v[206:209], v[18:21]
	v_mfma_f32_16x16x32_bf16 v[14:17], v[166:169], v[214:217], v[14:17]
	v_mfma_f32_16x16x32_bf16 v[10:13], v[178:181], v[214:217], v[10:13]
	v_mfma_f32_16x16x32_bf16 v[6:9], v[166:169], v[222:225], v[6:9]
	v_mfma_f32_16x16x32_bf16 v[2:5], v[178:181], v[222:225], v[2:5]
	v_mfma_f32_16x16x32_bf16 v[30:33], v[174:177], v[202:205], v[30:33]
	v_mfma_f32_16x16x32_bf16 v[26:29], v[182:185], v[202:205], v[26:29]
	v_mfma_f32_16x16x32_bf16 v[22:25], v[174:177], v[210:213], v[22:25]
	v_mfma_f32_16x16x32_bf16 v[18:21], v[182:185], v[210:213], v[18:21]
	v_mfma_f32_16x16x32_bf16 v[14:17], v[174:177], v[218:221], v[14:17]
	v_mfma_f32_16x16x32_bf16 v[10:13], v[182:185], v[218:221], v[10:13]
	v_mfma_f32_16x16x32_bf16 v[6:9], v[174:177], v[226:229], v[6:9]
	v_mfma_f32_16x16x32_bf16 v[2:5], v[182:185], v[226:229], v[2:5]
	s_setprio 0
	s_barrier
	s_add_i32 s30, s30, 2
	s_add_u32 s12, s12, 0x100
	s_addc_u32 s13, s13, 0
	s_add_u32 s18, s18, 0x100
	s_addc_u32 s19, s19, 0
	s_cmp_gt_u32 s30, 13

; #define PG8_STAGE(bufoff, gbase, voff) do { _Pragma("unroll") for (int _i = 0; _i < 2; ++_i) \
;         __builtin_amdgcn_global_load_lds((const unsigned*)((const char*)(gbase) + (voff)[_i]), (LAS unsigned*)(lds + (bufoff) + ldsw + _i * 8192), 16, 0, 0); } while (0)
; #define PG8_WAIT_V(n) asm volatile("s_waitcnt vmcnt(" #n ")" ::: "memory")
; #define PG8_BAR __builtin_amdgcn_s_barrier()
; template <class Epi, class Sched, bool ALIGN_EPI = true>
; __device__ __forceinline__ void gemm_phase(LAS unsigned char* lds, const int wave_s, const int K, const Sched& S, const Epi& E) {
;     ...
;     PG8_WAIT_V(2); PG8_BAR;
;     PG8_STAGE(PG8_SB(1, 0), cB + kstep, voffB); PG8_STAGE(PG8_SA(1, 0), cA + kstep, voffA); PG8_STAGE(PG8_SB(1, 1), cB + hstep + kstep, voffB);
;     PG8_WAIT_V(6); PG8_BAR;
.LBB0_416:
	s_add_u32 s50, s10, 0x6d00000
	s_addc_u32 s51, s11, 0
	s_add_u32 s54, s10, 0xed00000
	s_addc_u32 s55, s11, 0
	s_add_u32 s82, s10, 0x8d00000
	s_addc_u32 s83, s11, 0
	s_add_u32 s62, s10, 0x10d00000
	s_addc_u32 s63, s11, 0
	s_add_u32 s84, s10, 0xcd00000
	s_addc_u32 s85, s11, 0
	s_add_u32 s52, s10, 0xad00000
	s_addc_u32 s53, s11, 0
	s_add_u32 s94, s10, 0x12d00000
	s_addc_u32 s95, s11, 0
	v_lshl_add_u64 v[6:7], v[6:7], 0, s[22:23]
	s_add_i32 m0, s7, 0x18000
	s_waitcnt vmcnt(2)
	s_barrier
	global_load_lds_dwordx4 v[6:7], off
	v_lshl_add_u64 v[4:5], v[4:5], 0, s[22:23]
	s_add_i32 m0, s7, 0x1a000
	s_add_i32 s69, s7, 0x8000
	s_add_i32 s78, s7, 0xa000
	global_load_lds_dwordx4 v[4:5], off
	v_lshl_add_u64 v[2:3], v[2:3], 0, s[22:23]
	s_mov_b32 m0, s69
	s_add_u32 s14, s34, 0x40080
	global_load_lds_dwordx4 v[2:3], off
	v_lshl_add_u64 v[2:3], v[8:9], 0, s[22:23]
	s_mov_b32 m0, s78
	s_addc_u32 s15, s35, 0
	global_load_lds_dwordx4 v[2:3], off
	v_lshl_add_u64 v[2:3], s[14:15], 0, v[132:133]
	s_add_i32 m0, s7, 0x1c000
	s_mov_b32 s79, 0
	global_load_lds_dwordx4 v[2:3], off
	v_lshl_add_u64 v[2:3], s[14:15], 0, v[136:137]
	s_add_i32 m0, s7, 0x1e000
	v_readlane_b32 s14, v253, 6
	global_load_lds_dwordx4 v[2:3], off
	v_and_b32_e32 v2, 15, v13
	v_bfe_u32 v3, v13, 4, 2
	v_or_b32_e32 v174, s14, v2
	v_lshlrev_b32_e32 v4, 6, v174
	v_lshlrev_b32_e32 v6, 4, v3
	s_movk_i32 s14, 0x3c0
	v_lshlrev_b32_e32 v7, 2, v174
	v_and_or_b32 v4, v4, s14, v6
	v_and_b32_e32 v7, 32, v7
	v_readlane_b32 s14, v253, 7
	v_lshlrev_b32_e32 v5, 3, v3
	v_cmp_eq_u32_e64 s[42:43], 0, v3
	v_bitop3_b32 v7, v4, s14, v7 bitop3:0xde
	v_lshl_or_b32 v4, v2, 6, v6
	v_lshlrev_b32_e32 v2, 2, v2
	v_and_b32_e32 v6, 32, v2
	v_readlane_b32 s14, v253, 9
	s_waitcnt vmcnt(6)
	v_mov_b32_e32 v139, v1
	v_mov_b32_e32 v141, v1
	v_bitop3_b32 v175, v4, s14, v6 bitop3:0xde
	v_lshlrev_b32_e32 v4, 6, v3
	v_lshlrev_b32_e32 v3, 2, v3
	v_bitop3_b32 v176, v4, 64, v2 bitop3:0x36
	v_and_b32_e32 v4, 4, v3
	v_or_b32_e32 v6, 8, v3
	v_lshlrev_b32_e32 v3, 14, v0
	v_and_b32_e32 v3, 0xffff8000, v3
	v_lshl_add_u32 v3, v10, 11, v3
	v_and_b32_e32 v0, 1, v0
	v_lshl_or_b32 v0, v0, 6, v3
	v_lshl_add_u32 v138, v11, 1, v0
	v_lshlrev_b32_e32 v0, 14, v12
	v_and_b32_e32 v0, 0xffff8000, v0
	v_lshl_add_u32 v0, v14, 11, v0
	v_and_b32_e32 v3, 1, v12
	v_and_b32_e32 v2, 16, v5
	v_readlane_b32 s14, v253, 8
	v_lshl_or_b32 v0, v3, 6, v0
	v_lshl_add_u32 v140, v15, 1, v0
	v_or_b32_e32 v177, s14, v5
	v_add_u32_e32 v178, 0, v7
	v_lshlrev_b32_e32 v142, 1, v2
	v_lshlrev_b32_e32 v144, 1, v4
	v_lshlrev_b32_e32 v146, 1, v6
	s_barrier
	s_mov_b32 s100, 0
	s_branch .LBB0_419

; #define PG8_BAR __builtin_amdgcn_s_barrier()
; template <class Epi, class Sched, bool ALIGN_EPI = true>
; __device__ __forceinline__ void gemm_phase(LAS unsigned char* lds, const int wave_s, const int K, const Sched& S, const Epi& E) {
;     ...
;         if (!has_next) break;
; #pragma unroll
;         for (int a = 0; a < 2; ++a)
; #pragma unroll
;             for (int b = 0; b < 2; ++b)
; #pragma unroll
;                 for (int m = 0; m < 4; ++m)
; #pragma unroll
;                     for (int n = 0; n < 2; ++n) acc[a][b][m][n] = (f32x4){0.f, 0.f, 0.f, 0.f};
;         cur = nxt; cA = nA; cB = nB; ++ui;
;         if constexpr (ALIGN_EPI) { if (wr == 1) PG8_BAR; }
.LBB0_418:
	s_andn2_b64 vcc, exec, s[12:13]
	s_mov_b32 s16, s80
	s_mov_b32 s64, s14
	s_mov_b32 s18, s81
	s_mov_b64 s[34:35], s[90:91]
	s_mov_b64 s[12:13], s[70:71]
	s_cbranch_vccz .LBB0_569
	s_mov_b32 s100, 1

; template <class Epi, class Sched, bool ALIGN_EPI = true>
; __device__ __forceinline__ void gemm_phase(LAS unsigned char* lds, const int wave_s, const int K, const Sched& S, const Epi& E) {
;     ...
; #pragma unroll
;         for (int a = 0; a < 2; ++a)
; #pragma unroll
;             for (int b = 0; b < 2; ++b)
; #pragma unroll
;                 for (int m = 0; m < 4; ++m)
; #pragma unroll
;                     for (int n = 0; n < 2; ++n) acc[a][b][m][n] = (f32x4){0.f, 0.f, 0.f, 0.f};
;         cur = nxt; cA = nA; cB = nB; ++ui;
.LBB0_424:
	s_lshl_b32 s15, s81, 8
	s_addk_i32 s15, 0x1800
	s_cmp_eq_u32 s80, 0
	s_cselect_b32 s20, s81, s15
	s_cselect_b32 s15, 19, 11
	s_cselect_b32 s19, s5, s9
	s_cselect_b32 s28, s4, s8
	s_cselect_b32 s30, s8, s4
	s_cselect_b32 s36, s9, s5
	s_ashr_i32 s21, s20, 31
	s_lshl_b64 s[20:21], s[20:21], s15
	s_add_u32 s70, s28, s20
	s_addc_u32 s71, s19, s21
	s_and_b64 s[20:21], s[76:77], exec
	s_cselect_b32 s19, s71, s13
	s_cselect_b32 s20, s70, s12
	s_ashr_i32 s15, s14, 31
	s_lshl_b64 s[44:45], s[14:15], 19
	s_add_u32 s90, s30, s44
	s_addc_u32 s91, s36, s45
	s_and_b64 s[44:45], s[76:77], exec
	s_cselect_b32 s15, s91, s35
	s_cselect_b32 s21, s90, s34
	s_add_u32 s12, s12, 0x40080
	s_addc_u32 s13, s13, 0
	s_add_u32 s28, s34, 0x100
	v_mov_b32_e32 v2, 0
	s_addc_u32 s30, s35, 0
	s_mov_b32 s36, -2
	v_mov_b32_e32 v3, v2
	v_mov_b32_e32 v4, v2
	v_mov_b32_e32 v5, v2
	v_mov_b32_e32 v6, v2
	v_mov_b32_e32 v7, v2
	v_mov_b32_e32 v8, v2
	v_mov_b32_e32 v9, v2
	v_mov_b32_e32 v10, v2
	v_mov_b32_e32 v11, v2
	v_mov_b32_e32 v12, v2
	v_mov_b32_e32 v13, v2
	v_mov_b32_e32 v14, v2
	v_mov_b32_e32 v15, v2
	v_mov_b32_e32 v16, v2
	v_mov_b32_e32 v17, v2
	v_mov_b32_e32 v26, v2
	v_mov_b32_e32 v27, v2
	v_mov_b32_e32 v28, v2
	v_mov_b32_e32 v29, v2
	v_mov_b32_e32 v30, v2
	v_mov_b32_e32 v31, v2
	v_mov_b32_e32 v32, v2
	v_mov_b32_e32 v33, v2
	v_mov_b32_e32 v42, v2
	v_mov_b32_e32 v43, v2
	v_mov_b32_e32 v44, v2
	v_mov_b32_e32 v45, v2
	v_mov_b32_e32 v46, v2
	v_mov_b32_e32 v47, v2
	v_mov_b32_e32 v48, v2
	v_mov_b32_e32 v49, v2
	v_mov_b32_e32 v18, v2
	v_mov_b32_e32 v19, v2
	v_mov_b32_e32 v20, v2
	v_mov_b32_e32 v21, v2
	v_mov_b32_e32 v22, v2
	v_mov_b32_e32 v23, v2
	v_mov_b32_e32 v24, v2
	v_mov_b32_e32 v25, v2
	v_mov_b32_e32 v34, v2
	v_mov_b32_e32 v35, v2
	v_mov_b32_e32 v36, v2
	v_mov_b32_e32 v37, v2
	v_mov_b32_e32 v38, v2
	v_mov_b32_e32 v39, v2
	v_mov_b32_e32 v40, v2
	v_mov_b32_e32 v41, v2
	v_mov_b32_e32 v50, v2
	v_mov_b32_e32 v51, v2
	v_mov_b32_e32 v52, v2
	v_mov_b32_e32 v53, v2
	v_mov_b32_e32 v54, v2
	v_mov_b32_e32 v55, v2
	v_mov_b32_e32 v56, v2
	v_mov_b32_e32 v57, v2
	v_mov_b32_e32 v58, v2
	v_mov_b32_e32 v59, v2
	v_mov_b32_e32 v60, v2
	v_mov_b32_e32 v61, v2
	v_mov_b32_e32 v62, v2
	v_mov_b32_e32 v63, v2
	v_mov_b32_e32 v64, v2
	v_mov_b32_e32 v65, v2
	v_mov_b32_e32 v66, v2
	v_mov_b32_e32 v67, v2
	v_mov_b32_e32 v68, v2
	v_mov_b32_e32 v69, v2
	v_mov_b32_e32 v70, v2
	v_mov_b32_e32 v71, v2
	v_mov_b32_e32 v72, v2
	v_mov_b32_e32 v73, v2
	v_mov_b32_e32 v74, v2
	v_mov_b32_e32 v75, v2
	v_mov_b32_e32 v76, v2
	v_mov_b32_e32 v77, v2
	v_mov_b32_e32 v82, v2
	v_mov_b32_e32 v83, v2
	v_mov_b32_e32 v84, v2
	v_mov_b32_e32 v85, v2
	v_mov_b32_e32 v90, v2
	v_mov_b32_e32 v91, v2
	v_mov_b32_e32 v92, v2
	v_mov_b32_e32 v93, v2
	v_mov_b32_e32 v98, v2
	v_mov_b32_e32 v99, v2
	v_mov_b32_e32 v100, v2
	v_mov_b32_e32 v101, v2
	v_mov_b32_e32 v106, v2
	v_mov_b32_e32 v107, v2
	v_mov_b32_e32 v108, v2
	v_mov_b32_e32 v109, v2
	v_mov_b32_e32 v114, v2
	v_mov_b32_e32 v115, v2
	v_mov_b32_e32 v116, v2
	v_mov_b32_e32 v117, v2
	v_mov_b32_e32 v78, v2
	v_mov_b32_e32 v79, v2
	v_mov_b32_e32 v80, v2
	v_mov_b32_e32 v81, v2
	v_mov_b32_e32 v86, v2
	v_mov_b32_e32 v87, v2
	v_mov_b32_e32 v88, v2
	v_mov_b32_e32 v89, v2
	v_mov_b32_e32 v94, v2
	v_mov_b32_e32 v95, v2
	v_mov_b32_e32 v96, v2
	v_mov_b32_e32 v97, v2
	v_mov_b32_e32 v102, v2
	v_mov_b32_e32 v103, v2
	v_mov_b32_e32 v104, v2
	v_mov_b32_e32 v105, v2
	v_mov_b32_e32 v110, v2
	v_mov_b32_e32 v111, v2
	v_mov_b32_e32 v112, v2
	v_mov_b32_e32 v113, v2
	v_mov_b32_e32 v118, v2
	v_mov_b32_e32 v119, v2
	v_mov_b32_e32 v120, v2
	v_mov_b32_e32 v121, v2
	v_mov_b32_e32 v122, v2
	v_mov_b32_e32 v123, v2
	v_mov_b32_e32 v124, v2
	v_mov_b32_e32 v125, v2
	v_mov_b32_e32 v126, v2
	v_mov_b32_e32 v127, v2
	v_mov_b32_e32 v128, v2
	v_mov_b32_e32 v129, v2
	s_cmp_eq_u32 s100, 0
	s_cbranch_scc1 .LBB0_425
	s_add_u32 s34, s12, 0xfffc0080
	s_addc_u32 s35, s13, -1
	s_add_i32 s46, 0, 0x10000
	s_cmp_eq_u32 s36, 12
	s_cselect_b32 s45, s19, s35
	s_cselect_b32 s44, s20, s34
	v_add_u32_e32 v0, s46, v175
	s_cselect_b32 s35, s15, s30
	s_cselect_b32 s34, s21, s28
	s_add_i32 s48, 0, 0x14000
	ds_read_b128 v[148:151], v0
	ds_read_b128 v[152:155], v0 offset:1024
	ds_read_b128 v[156:159], v0 offset:2048
	ds_read_b128 v[166:169], v0 offset:3072
	v_add_u32_e32 v0, s48, v175
	ds_read_b128 v[170:173], v0
	ds_read_b128 v[180:183], v0 offset:1024
	ds_read_b128 v[184:187], v0 offset:2048
	ds_read_b128 v[188:191], v0 offset:3072
	v_lshl_add_u64 v[234:235], s[12:13], 0, v[138:139]
	s_add_i32 m0, s7, 0xc000
	ds_read_b128 v[202:205], v178
	ds_read_b128 v[206:209], v178 offset:1024
	ds_read_b128 v[210:213], v178 offset:2048
	ds_read_b128 v[214:217], v178 offset:3072
	ds_read_b128 v[218:221], v178 offset:4096
	ds_read_b128 v[222:225], v178 offset:5120
	ds_read_b128 v[226:229], v178 offset:6144
	ds_read_b128 v[230:233], v178 offset:7168
	global_load_lds_dwordx4 v[234:235], off
	v_lshl_add_u64 v[234:235], s[12:13], 0, v[140:141]
	s_add_i32 m0, s7, 0xe000
	s_nop 0
	global_load_lds_dwordx4 v[234:235], off
	s_waitcnt vmcnt(16)
	s_waitcnt lgkmcnt(0)
	s_barrier
; #define PG8_STAGE(bufoff, gbase, voff) do { _Pragma("unroll") for (int _i = 0; _i < 2; ++_i) \
;         __builtin_amdgcn_global_load_lds((const unsigned*)((const char*)(gbase) + (voff)[_i]), (LAS unsigned*)(lds + (bufoff) + ldsw + _i * 8192), 16, 0, 0); } while (0)
; #define PG8_LDA(dst, b, h) do { _Pragma("unroll") for (int m = 0; m < 4; ++m) _Pragma("unroll") for (int k = 0; k < 2; ++k) dst[m][k] = *(const LAS bf16x8*)(lds + PG8_SA(b, h) + aoff + m * 2048 + k * 1024); } while (0)
; #define PG8_MMA(ai, bj, At, Bt) do { __builtin_amdgcn_s_setprio(1); _Pragma("unroll") for (int m = 0; m < 4; ++m) _Pragma("unroll") for (int n = 0; n < 2; ++n) _Pragma("unroll") for (int k = 0; k < 2; ++k) \
;         acc[ai][bj][m][n] = __builtin_amdgcn_mfma_f32_16x16x32_bf16(Bt[n][k], At[m][k], acc[ai][bj][m][n], 0, 0, 0); __builtin_amdgcn_s_setprio(0); } while (0)
; #define PG8_WAIT_V(n) asm volatile("s_waitcnt vmcnt(" #n ")" ::: "memory")
; #define PG8_WAIT_L(n) asm volatile("s_waitcnt lgkmcnt(" #n ")" ::: "memory")
; #define PG8_BAR __builtin_amdgcn_s_barrier()
; #define PG8_SCHED __builtin_amdgcn_sched_barrier(0)
; template <class Epi, class Sched, bool ALIGN_EPI = true>
; __device__ __forceinline__ void gemm_phase(LAS unsigned char* lds, const int wave_s, const int K, const Sched& S, const Epi& E) {
;     ...
;             PG8_WAIT_V(8); PG8_WAIT_L(0); PG8_BAR; PG8_MMA(0, 0, At, B0); PG8_MMA(0, 1, At, B1); PG8_BAR; PG8_SCHED;
;             PG8_LDA(At, 0, 1); PG8_STAGE(PG8_SB(0, 0), b2, voffB); PG8_STAGE(PG8_SB(0, 1), b2 + hstep, voffB); PG8_STAGE(PG8_SA(0, 0), a2, voffA);
;             PG8_WAIT_V(8); PG8_WAIT_L(0); PG8_BAR; PG8_MMA(1, 0, At, B0); PG8_MMA(1, 1, At, B1); PG8_BAR; PG8_SCHED;
	s_setprio 1
	s_waitcnt lgkmcnt(0)
	v_mfma_f32_16x16x32_bf16 v[126:129], v[148:151], v[202:205], v[126:129]
	v_mfma_f32_16x16x32_bf16 v[122:125], v[156:159], v[202:205], v[122:125]
	v_mfma_f32_16x16x32_bf16 v[118:121], v[148:151], v[210:213], v[118:121]
	v_mfma_f32_16x16x32_bf16 v[110:113], v[156:159], v[210:213], v[110:113]
	v_mfma_f32_16x16x32_bf16 v[102:105], v[148:151], v[218:221], v[102:105]
	v_mfma_f32_16x16x32_bf16 v[94:97], v[156:159], v[218:221], v[94:97]
	v_mfma_f32_16x16x32_bf16 v[86:89], v[148:151], v[226:229], v[86:89]
	v_mfma_f32_16x16x32_bf16 v[78:81], v[156:159], v[226:229], v[78:81]
	v_mfma_f32_16x16x32_bf16 v[126:129], v[152:155], v[206:209], v[126:129]
	v_mfma_f32_16x16x32_bf16 v[122:125], v[166:169], v[206:209], v[122:125]
	v_mfma_f32_16x16x32_bf16 v[118:121], v[152:155], v[214:217], v[118:121]
	v_mfma_f32_16x16x32_bf16 v[110:113], v[166:169], v[214:217], v[110:113]
	v_mfma_f32_16x16x32_bf16 v[102:105], v[152:155], v[222:225], v[102:105]
	v_mfma_f32_16x16x32_bf16 v[94:97], v[166:169], v[222:225], v[94:97]
	v_mfma_f32_16x16x32_bf16 v[86:89], v[152:155], v[230:233], v[86:89]
	v_mfma_f32_16x16x32_bf16 v[78:81], v[166:169], v[230:233], v[78:81]
	s_setprio 0
	s_setprio 1
	v_mfma_f32_16x16x32_bf16 v[114:117], v[170:173], v[202:205], v[114:117]
	v_mfma_f32_16x16x32_bf16 v[106:109], v[184:187], v[202:205], v[106:109]
	v_mfma_f32_16x16x32_bf16 v[98:101], v[170:173], v[210:213], v[98:101]
	v_mfma_f32_16x16x32_bf16 v[90:93], v[184:187], v[210:213], v[90:93]
	v_mfma_f32_16x16x32_bf16 v[82:85], v[170:173], v[218:221], v[82:85]
	v_mfma_f32_16x16x32_bf16 v[74:77], v[184:187], v[218:221], v[74:77]
	v_mfma_f32_16x16x32_bf16 v[70:73], v[170:173], v[226:229], v[70:73]
	v_mfma_f32_16x16x32_bf16 v[66:69], v[184:187], v[226:229], v[66:69]
	v_mfma_f32_16x16x32_bf16 v[114:117], v[180:183], v[206:209], v[114:117]
	v_mfma_f32_16x16x32_bf16 v[106:109], v[188:191], v[206:209], v[106:109]
	v_mfma_f32_16x16x32_bf16 v[98:101], v[180:183], v[214:217], v[98:101]
	v_mfma_f32_16x16x32_bf16 v[90:93], v[188:191], v[214:217], v[90:93]
	v_mfma_f32_16x16x32_bf16 v[82:85], v[180:183], v[222:225], v[82:85]
	v_mfma_f32_16x16x32_bf16 v[74:77], v[188:191], v[222:225], v[74:77]
	v_mfma_f32_16x16x32_bf16 v[70:73], v[180:183], v[230:233], v[70:73]
	v_mfma_f32_16x16x32_bf16 v[66:69], v[188:191], v[230:233], v[66:69]
	s_setprio 0
	s_barrier
	s_add_i32 s46, s46, s33
	v_lshl_add_u64 v[234:235], s[34:35], 0, v[132:133]
	s_mov_b32 m0, s46
	ds_read_b128 v[202:205], v178 offset:16384
	ds_read_b128 v[206:209], v178 offset:17408
	ds_read_b128 v[210:213], v178 offset:18432
	ds_read_b128 v[214:217], v178 offset:19456
	ds_read_b128 v[218:221], v178 offset:20480
	ds_read_b128 v[222:225], v178 offset:21504
	ds_read_b128 v[226:229], v178 offset:22528
	ds_read_b128 v[230:233], v178 offset:23552
	global_load_lds_dwordx4 v[234:235], off
	s_add_i32 m0, s46, 0x2000
	s_add_u32 s46, s34, 0x40000
	v_lshl_add_u64 v[236:237], s[34:35], 0, v[136:137]
	s_addc_u32 s47, s35, 0
	s_add_i32 s48, s48, s33
	global_load_lds_dwordx4 v[236:237], off
	v_lshl_add_u64 v[238:239], s[46:47], 0, v[132:133]
	s_mov_b32 m0, s48
	v_lshl_add_u64 v[240:241], s[44:45], 0, v[134:135]
	global_load_lds_dwordx4 v[238:239], off
	v_lshl_add_u64 v[238:239], s[46:47], 0, v[136:137]
	s_add_i32 m0, s48, 0x2000
	s_nop 0
	global_load_lds_dwordx4 v[238:239], off
	v_lshl_add_u64 v[238:239], s[44:45], 0, v[130:131]
	s_mov_b32 m0, s7
	s_nop 0
	global_load_lds_dwordx4 v[238:239], off
	s_mov_b32 m0, s39
	s_nop 0
	global_load_lds_dwordx4 v[240:241], off
	s_waitcnt vmcnt(16)
	s_waitcnt lgkmcnt(0)
	s_barrier
	s_setprio 1
	s_waitcnt lgkmcnt(0)
	v_mfma_f32_16x16x32_bf16 v[62:65], v[148:151], v[202:205], v[62:65]
	v_mfma_f32_16x16x32_bf16 v[58:61], v[156:159], v[202:205], v[58:61]
	v_mfma_f32_16x16x32_bf16 v[54:57], v[148:151], v[210:213], v[54:57]
	v_mfma_f32_16x16x32_bf16 v[50:53], v[156:159], v[210:213], v[50:53]
	v_mfma_f32_16x16x32_bf16 v[38:41], v[148:151], v[218:221], v[38:41]
	v_mfma_f32_16x16x32_bf16 v[34:37], v[156:159], v[218:221], v[34:37]
	v_mfma_f32_16x16x32_bf16 v[22:25], v[148:151], v[226:229], v[22:25]
	v_mfma_f32_16x16x32_bf16 v[18:21], v[156:159], v[226:229], v[18:21]
	v_mfma_f32_16x16x32_bf16 v[62:65], v[152:155], v[206:209], v[62:65]
	v_mfma_f32_16x16x32_bf16 v[58:61], v[166:169], v[206:209], v[58:61]
	v_mfma_f32_16x16x32_bf16 v[54:57], v[152:155], v[214:217], v[54:57]
	v_mfma_f32_16x16x32_bf16 v[50:53], v[166:169], v[214:217], v[50:53]
	v_mfma_f32_16x16x32_bf16 v[38:41], v[152:155], v[222:225], v[38:41]
	v_mfma_f32_16x16x32_bf16 v[34:37], v[166:169], v[222:225], v[34:37]
	v_mfma_f32_16x16x32_bf16 v[22:25], v[152:155], v[230:233], v[22:25]
	v_mfma_f32_16x16x32_bf16 v[18:21], v[166:169], v[230:233], v[18:21]
	s_setprio 0
	s_setprio 1
	v_mfma_f32_16x16x32_bf16 v[46:49], v[170:173], v[202:205], v[46:49]
	v_mfma_f32_16x16x32_bf16 v[42:45], v[184:187], v[202:205], v[42:45]
	v_mfma_f32_16x16x32_bf16 v[30:33], v[170:173], v[210:213], v[30:33]
	v_mfma_f32_16x16x32_bf16 v[26:29], v[184:187], v[210:213], v[26:29]
	v_mfma_f32_16x16x32_bf16 v[14:17], v[170:173], v[218:221], v[14:17]
	v_mfma_f32_16x16x32_bf16 v[10:13], v[184:187], v[218:221], v[10:13]
	v_mfma_f32_16x16x32_bf16 v[6:9], v[170:173], v[226:229], v[6:9]
	v_mfma_f32_16x16x32_bf16 v[2:5], v[184:187], v[226:229], v[2:5]
	v_mfma_f32_16x16x32_bf16 v[46:49], v[180:183], v[206:209], v[46:49]
	v_mfma_f32_16x16x32_bf16 v[42:45], v[188:191], v[206:209], v[42:45]
	v_mfma_f32_16x16x32_bf16 v[30:33], v[180:183], v[214:217], v[30:33]
	v_mfma_f32_16x16x32_bf16 v[26:29], v[188:191], v[214:217], v[26:29]
	v_mfma_f32_16x16x32_bf16 v[14:17], v[180:183], v[222:225], v[14:17]
	v_mfma_f32_16x16x32_bf16 v[10:13], v[188:191], v[222:225], v[10:13]
	v_mfma_f32_16x16x32_bf16 v[6:9], v[180:183], v[230:233], v[6:9]
	v_mfma_f32_16x16x32_bf16 v[2:5], v[188:191], v[230:233], v[2:5]
	s_setprio 0
	s_barrier
; #define PG8_STAGE(bufoff, gbase, voff) do { _Pragma("unroll") for (int _i = 0; _i < 2; ++_i) \
;         __builtin_amdgcn_global_load_lds((const unsigned*)((const char*)(gbase) + (voff)[_i]), (LAS unsigned*)(lds + (bufoff) + ldsw + _i * 8192), 16, 0, 0); } while (0)
; #define PG8_LDA(dst, b, h) do { _Pragma("unroll") for (int m = 0; m < 4; ++m) _Pragma("unroll") for (int k = 0; k < 2; ++k) dst[m][k] = *(const LAS bf16x8*)(lds + PG8_SA(b, h) + aoff + m * 2048 + k * 1024); } while (0)
; #define PG8_LDB(dst, b, h) do { _Pragma("unroll") for (int n = 0; n < 2; ++n) _Pragma("unroll") for (int k = 0; k < 2; ++k) dst[n][k] = *(const LAS bf16x8*)(lds + PG8_SB(b, h) + boff + n * 2048 + k * 1024); } while (0)
; #define PG8_MMA(ai, bj, At, Bt) do { __builtin_amdgcn_s_setprio(1); _Pragma("unroll") for (int m = 0; m < 4; ++m) _Pragma("unroll") for (int n = 0; n < 2; ++n) _Pragma("unroll") for (int k = 0; k < 2; ++k) \
;         acc[ai][bj][m][n] = __builtin_amdgcn_mfma_f32_16x16x32_bf16(Bt[n][k], At[m][k], acc[ai][bj][m][n], 0, 0, 0); __builtin_amdgcn_s_setprio(0); } while (0)
; #define PG8_WAIT_V(n) asm volatile("s_waitcnt vmcnt(" #n ")" ::: "memory")
; #define PG8_WAIT_L(n) asm volatile("s_waitcnt lgkmcnt(" #n ")" ::: "memory")
; #define PG8_BAR __builtin_amdgcn_s_barrier()
; #define PG8_SCHED __builtin_amdgcn_sched_barrier(0)
; template <class Epi, class Sched, bool ALIGN_EPI = true>
; __device__ __forceinline__ void gemm_phase(LAS unsigned char* lds, const int wave_s, const int K, const Sched& S, const Epi& E) {
;     ...
;             PG8_LDB(B0, 1, 0); PG8_LDB(B1, 1, 1); PG8_SCHED; PG8_LDA(At, 1, 0); PG8_STAGE(PG8_SA(0, 1), a2 + hstep, voffA);
;             PG8_WAIT_V(8); PG8_WAIT_L(0); PG8_BAR; PG8_MMA(0, 0, At, B0); PG8_MMA(0, 1, At, B1); PG8_BAR; PG8_SCHED;
	s_add_i32 s46, 0, 0x18000
	v_add_u32_e32 v0, s46, v175
	s_add_i32 s47, 0, 0x1c000
	ds_read_b128 v[148:151], v0
	ds_read_b128 v[152:155], v0 offset:1024
	ds_read_b128 v[156:159], v0 offset:2048
	ds_read_b128 v[166:169], v0 offset:3072
	v_add_u32_e32 v0, s47, v175
	ds_read_b128 v[170:173], v0
	ds_read_b128 v[180:183], v0 offset:1024
	ds_read_b128 v[184:187], v0 offset:2048
	ds_read_b128 v[188:191], v0 offset:3072
	s_add_u32 s44, s44, 0x40000
	s_addc_u32 s45, s45, 0
	s_mov_b32 m0, s65
	v_lshl_add_u64 v[242:243], s[44:45], 0, v[130:131]
	ds_read_b128 v[202:205], v178 offset:32768
	ds_read_b128 v[206:209], v178 offset:33792
	ds_read_b128 v[210:213], v178 offset:34816
	ds_read_b128 v[214:217], v178 offset:35840
	ds_read_b128 v[218:221], v178 offset:36864
	ds_read_b128 v[222:225], v178 offset:37888
	ds_read_b128 v[226:229], v178 offset:38912
	ds_read_b128 v[230:233], v178 offset:39936
	global_load_lds_dwordx4 v[242:243], off
	v_lshl_add_u64 v[242:243], s[44:45], 0, v[134:135]
	s_mov_b32 m0, s68
	s_nop 0
	global_load_lds_dwordx4 v[242:243], off
	s_waitcnt vmcnt(16)
	s_waitcnt lgkmcnt(0)
	s_barrier
	s_setprio 1
	s_waitcnt lgkmcnt(0)
	v_mfma_f32_16x16x32_bf16 v[126:129], v[148:151], v[202:205], v[126:129]
	v_mfma_f32_16x16x32_bf16 v[122:125], v[156:159], v[202:205], v[122:125]
	v_mfma_f32_16x16x32_bf16 v[118:121], v[148:151], v[210:213], v[118:121]
	v_mfma_f32_16x16x32_bf16 v[110:113], v[156:159], v[210:213], v[110:113]
	v_mfma_f32_16x16x32_bf16 v[102:105], v[148:151], v[218:221], v[102:105]
	v_mfma_f32_16x16x32_bf16 v[94:97], v[156:159], v[218:221], v[94:97]
	v_mfma_f32_16x16x32_bf16 v[86:89], v[148:151], v[226:229], v[86:89]
	v_mfma_f32_16x16x32_bf16 v[78:81], v[156:159], v[226:229], v[78:81]
	v_mfma_f32_16x16x32_bf16 v[126:129], v[152:155], v[206:209], v[126:129]
	v_mfma_f32_16x16x32_bf16 v[122:125], v[166:169], v[206:209], v[122:125]
	v_mfma_f32_16x16x32_bf16 v[118:121], v[152:155], v[214:217], v[118:121]
	v_mfma_f32_16x16x32_bf16 v[110:113], v[166:169], v[214:217], v[110:113]
	v_mfma_f32_16x16x32_bf16 v[102:105], v[152:155], v[222:225], v[102:105]
	v_mfma_f32_16x16x32_bf16 v[94:97], v[166:169], v[222:225], v[94:97]
	v_mfma_f32_16x16x32_bf16 v[86:89], v[152:155], v[230:233], v[86:89]
	v_mfma_f32_16x16x32_bf16 v[78:81], v[166:169], v[230:233], v[78:81]
	s_setprio 0
	s_setprio 1
	v_mfma_f32_16x16x32_bf16 v[114:117], v[170:173], v[202:205], v[114:117]
	v_mfma_f32_16x16x32_bf16 v[106:109], v[184:187], v[202:205], v[106:109]
	v_mfma_f32_16x16x32_bf16 v[98:101], v[170:173], v[210:213], v[98:101]
	v_mfma_f32_16x16x32_bf16 v[90:93], v[184:187], v[210:213], v[90:93]
	v_mfma_f32_16x16x32_bf16 v[82:85], v[170:173], v[218:221], v[82:85]
	v_mfma_f32_16x16x32_bf16 v[74:77], v[184:187], v[218:221], v[74:77]
	v_mfma_f32_16x16x32_bf16 v[70:73], v[170:173], v[226:229], v[70:73]
	v_mfma_f32_16x16x32_bf16 v[66:69], v[184:187], v[226:229], v[66:69]
	v_mfma_f32_16x16x32_bf16 v[114:117], v[180:183], v[206:209], v[114:117]
	v_mfma_f32_16x16x32_bf16 v[106:109], v[188:191], v[206:209], v[106:109]
	v_mfma_f32_16x16x32_bf16 v[98:101], v[180:183], v[214:217], v[98:101]
	v_mfma_f32_16x16x32_bf16 v[90:93], v[188:191], v[214:217], v[90:93]
	v_mfma_f32_16x16x32_bf16 v[82:85], v[180:183], v[222:225], v[82:85]
	v_mfma_f32_16x16x32_bf16 v[74:77], v[188:191], v[222:225], v[74:77]
	v_mfma_f32_16x16x32_bf16 v[70:73], v[180:183], v[230:233], v[70:73]
	v_mfma_f32_16x16x32_bf16 v[66:69], v[188:191], v[230:233], v[66:69]
	s_setprio 0
	s_barrier
; #define PG8_STAGE(bufoff, gbase, voff) do { _Pragma("unroll") for (int _i = 0; _i < 2; ++_i) \
;         __builtin_amdgcn_global_load_lds((const unsigned*)((const char*)(gbase) + (voff)[_i]), (LAS unsigned*)(lds + (bufoff) + ldsw + _i * 8192), 16, 0, 0); } while (0)
; #define PG8_LDA(dst, b, h) do { _Pragma("unroll") for (int m = 0; m < 4; ++m) _Pragma("unroll") for (int k = 0; k < 2; ++k) dst[m][k] = *(const LAS bf16x8*)(lds + PG8_SA(b, h) + aoff + m * 2048 + k * 1024); } while (0)
; #define PG8_MMA(ai, bj, At, Bt) do { __builtin_amdgcn_s_setprio(1); _Pragma("unroll") for (int m = 0; m < 4; ++m) _Pragma("unroll") for (int n = 0; n < 2; ++n) _Pragma("unroll") for (int k = 0; k < 2; ++k) \
;         acc[ai][bj][m][n] = __builtin_amdgcn_mfma_f32_16x16x32_bf16(Bt[n][k], At[m][k], acc[ai][bj][m][n], 0, 0, 0); __builtin_amdgcn_s_setprio(0); } while (0)
; #define PG8_WAIT_V(n) asm volatile("s_waitcnt vmcnt(" #n ")" ::: "memory")
; #define PG8_WAIT_L(n) asm volatile("s_waitcnt lgkmcnt(" #n ")" ::: "memory")
; #define PG8_BAR __builtin_amdgcn_s_barrier()
; #define PG8_SCHED __builtin_amdgcn_sched_barrier(0)
; template <class Epi, class Sched, bool ALIGN_EPI = true>
; __device__ __forceinline__ void gemm_phase(LAS unsigned char* lds, const int wave_s, const int K, const Sched& S, const Epi& E) {
;     ...
;             PG8_LDA(At, 1, 1); PG8_STAGE(PG8_SB(1, 0), b3, voffB); PG8_STAGE(PG8_SB(1, 1), b3 + hstep, voffB); PG8_STAGE(PG8_SA(1, 0), a3, voffA);
;             PG8_WAIT_V(8); PG8_WAIT_L(0); PG8_BAR; PG8_MMA(1, 0, At, B0); PG8_MMA(1, 1, At, B1); PG8_BAR; PG8_SCHED;
	s_add_i32 s44, s46, s33
	v_lshl_add_u64 v[234:235], v[234:235], 0, s[22:23]
	s_mov_b32 m0, s44
	ds_read_b128 v[202:205], v178 offset:49152
	ds_read_b128 v[206:209], v178 offset:50176
	ds_read_b128 v[210:213], v178 offset:51200
	ds_read_b128 v[214:217], v178 offset:52224
	ds_read_b128 v[218:221], v178 offset:53248
	ds_read_b128 v[222:225], v178 offset:54272
	ds_read_b128 v[226:229], v178 offset:55296
	ds_read_b128 v[230:233], v178 offset:56320
	global_load_lds_dwordx4 v[234:235], off
	s_add_i32 m0, s44, 0x2000
	s_add_u32 s34, s34, 0x40080
	v_lshl_add_u64 v[234:235], v[236:237], 0, s[22:23]
	s_addc_u32 s35, s35, 0
	s_add_i32 s44, s47, s33
	global_load_lds_dwordx4 v[234:235], off
	v_lshl_add_u64 v[234:235], s[34:35], 0, v[132:133]
	s_mov_b32 m0, s44
	s_nop 0
	global_load_lds_dwordx4 v[234:235], off
	v_lshl_add_u64 v[234:235], s[34:35], 0, v[136:137]
	s_add_i32 m0, s44, 0x2000
	s_nop 0
	global_load_lds_dwordx4 v[234:235], off
	v_lshl_add_u64 v[234:235], v[238:239], 0, s[22:23]
	s_mov_b32 m0, s69
	s_nop 0
	global_load_lds_dwordx4 v[234:235], off
	v_lshl_add_u64 v[234:235], v[240:241], 0, s[22:23]
	s_mov_b32 m0, s78
	s_nop 0
	global_load_lds_dwordx4 v[234:235], off
	s_waitcnt vmcnt(16)
	s_waitcnt lgkmcnt(0)
	s_barrier
	s_setprio 1
	s_waitcnt lgkmcnt(0)
	v_mfma_f32_16x16x32_bf16 v[62:65], v[148:151], v[202:205], v[62:65]
	v_mfma_f32_16x16x32_bf16 v[58:61], v[156:159], v[202:205], v[58:61]
	v_mfma_f32_16x16x32_bf16 v[54:57], v[148:151], v[210:213], v[54:57]
	v_mfma_f32_16x16x32_bf16 v[50:53], v[156:159], v[210:213], v[50:53]
	v_mfma_f32_16x16x32_bf16 v[38:41], v[148:151], v[218:221], v[38:41]
	v_mfma_f32_16x16x32_bf16 v[34:37], v[156:159], v[218:221], v[34:37]
	v_mfma_f32_16x16x32_bf16 v[22:25], v[148:151], v[226:229], v[22:25]
	v_mfma_f32_16x16x32_bf16 v[18:21], v[156:159], v[226:229], v[18:21]
	v_mfma_f32_16x16x32_bf16 v[62:65], v[152:155], v[206:209], v[62:65]
	v_mfma_f32_16x16x32_bf16 v[58:61], v[166:169], v[206:209], v[58:61]
	v_mfma_f32_16x16x32_bf16 v[54:57], v[152:155], v[214:217], v[54:57]
	v_mfma_f32_16x16x32_bf16 v[50:53], v[166:169], v[214:217], v[50:53]
	v_mfma_f32_16x16x32_bf16 v[38:41], v[152:155], v[222:225], v[38:41]
	v_mfma_f32_16x16x32_bf16 v[34:37], v[166:169], v[222:225], v[34:37]
	v_mfma_f32_16x16x32_bf16 v[22:25], v[152:155], v[230:233], v[22:25]
	v_mfma_f32_16x16x32_bf16 v[18:21], v[166:169], v[230:233], v[18:21]
	s_setprio 0
	s_setprio 1
	v_mfma_f32_16x16x32_bf16 v[46:49], v[170:173], v[202:205], v[46:49]
	v_mfma_f32_16x16x32_bf16 v[42:45], v[184:187], v[202:205], v[42:45]
	v_mfma_f32_16x16x32_bf16 v[30:33], v[170:173], v[210:213], v[30:33]
	v_mfma_f32_16x16x32_bf16 v[26:29], v[184:187], v[210:213], v[26:29]
	v_mfma_f32_16x16x32_bf16 v[14:17], v[170:173], v[218:221], v[14:17]
	v_mfma_f32_16x16x32_bf16 v[10:13], v[184:187], v[218:221], v[10:13]
	v_mfma_f32_16x16x32_bf16 v[6:9], v[170:173], v[226:229], v[6:9]
	v_mfma_f32_16x16x32_bf16 v[2:5], v[184:187], v[226:229], v[2:5]
	v_mfma_f32_16x16x32_bf16 v[46:49], v[180:183], v[206:209], v[46:49]
	v_mfma_f32_16x16x32_bf16 v[42:45], v[188:191], v[206:209], v[42:45]
	v_mfma_f32_16x16x32_bf16 v[30:33], v[180:183], v[214:217], v[30:33]
	v_mfma_f32_16x16x32_bf16 v[26:29], v[188:191], v[214:217], v[26:29]
	v_mfma_f32_16x16x32_bf16 v[14:17], v[180:183], v[222:225], v[14:17]
	v_mfma_f32_16x16x32_bf16 v[10:13], v[188:191], v[222:225], v[10:13]
	v_mfma_f32_16x16x32_bf16 v[6:9], v[180:183], v[230:233], v[6:9]
	v_mfma_f32_16x16x32_bf16 v[2:5], v[188:191], v[230:233], v[2:5]
	s_setprio 0
	s_barrier
	s_add_i32 s36, s36, 2
	s_add_u32 s12, s12, 0x100
	s_addc_u32 s13, s13, 0
	s_add_u32 s28, s28, 0x100
	s_addc_u32 s30, s30, 0
	s_cmp_gt_u32 s36, 13
